# adds hand-written SwiGLU epilogue (same per-element arithmetic, 8-wide steps, packed multiplies, row scales read up front) to v018
# speedup vs baseline: 1.0259x; 1.0028x over previous
.LBB0_479:
	v_lshl_add_u32 v160, s12, 10, v153
	v_lshl_or_b32 v150, s13, 7, v154
	v_lshl_add_u32 v159, s40, 8, v131
	v_ashrrev_i32_e32 v151, 31, v150
	v_mov_b64_e32 v[148:149], s[16:17]
	v_mad_i64_i32 v[164:165], s[12:13], v159, s67, v[148:149]
	v_lshlrev_b64 v[150:151], 1, v[150:151]
	v_lshl_add_u64 v[164:165], v[164:165], 0, v[150:151]
	v_mov_b32_e32 v232, v164
	v_mov_b32_e32 v233, v165
	ds_read_b32 v172, v160
	ds_read_b32 v174, v160 offset:64
	ds_read_b32 v176, v160 offset:128
	ds_read_b32 v178, v160 offset:192
	ds_read_b32 v180, v160 offset:512
	ds_read_b32 v182, v160 offset:576
	ds_read_b32 v184, v160 offset:640
	ds_read_b32 v186, v160 offset:704
	v_mov_b32_e32 v188, 0xbfb8aa3b
	s_waitcnt lgkmcnt(7)
	v_pk_mul_f32 v[124:125], v[124:125], v[172:173] op_sel_hi:[1,0]
	v_pk_mul_f32 v[126:127], v[126:127], v[172:173] op_sel_hi:[1,0]
	v_pk_mul_f32 v[120:121], v[120:121], v[172:173] op_sel_hi:[1,0]
	v_pk_mul_f32 v[122:123], v[122:123], v[172:173] op_sel_hi:[1,0]
	v_pk_mul_f32 v[116:117], v[116:117], v[172:173] op_sel_hi:[1,0]
	v_pk_mul_f32 v[118:119], v[118:119], v[172:173] op_sel_hi:[1,0]
	v_pk_mul_f32 v[112:113], v[112:113], v[172:173] op_sel_hi:[1,0]
	v_pk_mul_f32 v[114:115], v[114:115], v[172:173] op_sel_hi:[1,0]
	v_pk_mul_f32 v[192:193], v[124:125], v[188:189] op_sel_hi:[1,0]
	v_pk_mul_f32 v[194:195], v[126:127], v[188:189] op_sel_hi:[1,0]
	v_pk_mul_f32 v[196:197], v[120:121], v[188:189] op_sel_hi:[1,0]
	v_pk_mul_f32 v[198:199], v[122:123], v[188:189] op_sel_hi:[1,0]
	v_exp_f32_e32 v192, v192
	v_exp_f32_e32 v193, v193
	v_exp_f32_e32 v194, v194
	v_exp_f32_e32 v195, v195
	v_exp_f32_e32 v196, v196
	v_exp_f32_e32 v197, v197
	v_exp_f32_e32 v198, v198
	v_exp_f32_e32 v199, v199
	v_add_f32_e32 v192, 1.0, v192
	v_add_f32_e32 v193, 1.0, v193
	v_add_f32_e32 v194, 1.0, v194
	v_add_f32_e32 v195, 1.0, v195
	v_add_f32_e32 v196, 1.0, v196
	v_add_f32_e32 v197, 1.0, v197
	v_add_f32_e32 v198, 1.0, v198
	v_add_f32_e32 v199, 1.0, v199
	v_rcp_f32_e32 v192, v192
	v_rcp_f32_e32 v193, v193
	v_rcp_f32_e32 v194, v194
	v_rcp_f32_e32 v195, v195
	v_rcp_f32_e32 v196, v196
	v_rcp_f32_e32 v197, v197
	v_rcp_f32_e32 v198, v198
	v_rcp_f32_e32 v199, v199
	v_pk_mul_f32 v[124:125], v[124:125], v[192:193]
	v_pk_mul_f32 v[126:127], v[126:127], v[194:195]
	v_pk_mul_f32 v[120:121], v[120:121], v[196:197]
	v_pk_mul_f32 v[122:123], v[122:123], v[198:199]
	v_pk_mul_f32 v[124:125], v[116:117], v[124:125]
	v_pk_mul_f32 v[126:127], v[118:119], v[126:127]
	v_pk_mul_f32 v[120:121], v[112:113], v[120:121]
	v_pk_mul_f32 v[122:123], v[114:115], v[122:123]
	v_cvt_pk_bf16_f32 v208, v124, v125
	v_cvt_pk_bf16_f32 v209, v126, v127
	v_cvt_pk_bf16_f32 v210, v120, v121
	v_cvt_pk_bf16_f32 v211, v122, v123
	global_store_dwordx4 v[232:233], v[208:211], off
	s_waitcnt lgkmcnt(6)
	v_pk_mul_f32 v[108:109], v[108:109], v[174:175] op_sel_hi:[1,0]
	v_pk_mul_f32 v[110:111], v[110:111], v[174:175] op_sel_hi:[1,0]
	v_pk_mul_f32 v[104:105], v[104:105], v[174:175] op_sel_hi:[1,0]
	v_pk_mul_f32 v[106:107], v[106:107], v[174:175] op_sel_hi:[1,0]
	v_pk_mul_f32 v[100:101], v[100:101], v[174:175] op_sel_hi:[1,0]
	v_pk_mul_f32 v[102:103], v[102:103], v[174:175] op_sel_hi:[1,0]
	v_pk_mul_f32 v[96:97], v[96:97], v[174:175] op_sel_hi:[1,0]
	v_pk_mul_f32 v[98:99], v[98:99], v[174:175] op_sel_hi:[1,0]
	v_pk_mul_f32 v[200:201], v[108:109], v[188:189] op_sel_hi:[1,0]
	v_pk_mul_f32 v[202:203], v[110:111], v[188:189] op_sel_hi:[1,0]
	v_pk_mul_f32 v[204:205], v[104:105], v[188:189] op_sel_hi:[1,0]
	v_pk_mul_f32 v[206:207], v[106:107], v[188:189] op_sel_hi:[1,0]
	v_exp_f32_e32 v200, v200
	v_exp_f32_e32 v201, v201
	v_exp_f32_e32 v202, v202
	v_exp_f32_e32 v203, v203
	v_exp_f32_e32 v204, v204
	v_exp_f32_e32 v205, v205
	v_exp_f32_e32 v206, v206
	v_exp_f32_e32 v207, v207
	v_add_f32_e32 v200, 1.0, v200
	v_add_f32_e32 v201, 1.0, v201
	v_add_f32_e32 v202, 1.0, v202
	v_add_f32_e32 v203, 1.0, v203
	v_add_f32_e32 v204, 1.0, v204
	v_add_f32_e32 v205, 1.0, v205
	v_add_f32_e32 v206, 1.0, v206
	v_add_f32_e32 v207, 1.0, v207
	v_rcp_f32_e32 v200, v200
	v_rcp_f32_e32 v201, v201
	v_rcp_f32_e32 v202, v202
	v_rcp_f32_e32 v203, v203
	v_rcp_f32_e32 v204, v204
	v_rcp_f32_e32 v205, v205
	v_rcp_f32_e32 v206, v206
	v_rcp_f32_e32 v207, v207
	v_pk_mul_f32 v[108:109], v[108:109], v[200:201]
	v_pk_mul_f32 v[110:111], v[110:111], v[202:203]
	v_pk_mul_f32 v[104:105], v[104:105], v[204:205]
	v_pk_mul_f32 v[106:107], v[106:107], v[206:207]
	v_pk_mul_f32 v[108:109], v[100:101], v[108:109]
	v_pk_mul_f32 v[110:111], v[102:103], v[110:111]
	v_pk_mul_f32 v[104:105], v[96:97], v[104:105]
	v_pk_mul_f32 v[106:107], v[98:99], v[106:107]
	v_cvt_pk_bf16_f32 v212, v108, v109
	v_cvt_pk_bf16_f32 v213, v110, v111
	v_cvt_pk_bf16_f32 v214, v104, v105
	v_cvt_pk_bf16_f32 v215, v106, v107
	s_mov_b64 s[100:101], 0x16000
	v_lshl_add_u64 v[216:217], v[232:233], 0, s[100:101]
	global_store_dwordx4 v[216:217], v[212:215], off
	s_waitcnt lgkmcnt(5)
	v_pk_mul_f32 v[92:93], v[92:93], v[176:177] op_sel_hi:[1,0]
	v_pk_mul_f32 v[94:95], v[94:95], v[176:177] op_sel_hi:[1,0]
	v_pk_mul_f32 v[88:89], v[88:89], v[176:177] op_sel_hi:[1,0]
	v_pk_mul_f32 v[90:91], v[90:91], v[176:177] op_sel_hi:[1,0]
	v_pk_mul_f32 v[84:85], v[84:85], v[176:177] op_sel_hi:[1,0]
	v_pk_mul_f32 v[86:87], v[86:87], v[176:177] op_sel_hi:[1,0]
	v_pk_mul_f32 v[80:81], v[80:81], v[176:177] op_sel_hi:[1,0]
	v_pk_mul_f32 v[82:83], v[82:83], v[176:177] op_sel_hi:[1,0]
	v_pk_mul_f32 v[192:193], v[92:93], v[188:189] op_sel_hi:[1,0]
	v_pk_mul_f32 v[194:195], v[94:95], v[188:189] op_sel_hi:[1,0]
	v_pk_mul_f32 v[196:197], v[88:89], v[188:189] op_sel_hi:[1,0]
	v_pk_mul_f32 v[198:199], v[90:91], v[188:189] op_sel_hi:[1,0]
	v_exp_f32_e32 v192, v192
	v_exp_f32_e32 v193, v193
	v_exp_f32_e32 v194, v194
	v_exp_f32_e32 v195, v195
	v_exp_f32_e32 v196, v196
	v_exp_f32_e32 v197, v197
	v_exp_f32_e32 v198, v198
	v_exp_f32_e32 v199, v199
	v_add_f32_e32 v192, 1.0, v192
	v_add_f32_e32 v193, 1.0, v193
	v_add_f32_e32 v194, 1.0, v194
	v_add_f32_e32 v195, 1.0, v195
	v_add_f32_e32 v196, 1.0, v196
	v_add_f32_e32 v197, 1.0, v197
	v_add_f32_e32 v198, 1.0, v198
	v_add_f32_e32 v199, 1.0, v199
	v_rcp_f32_e32 v192, v192
	v_rcp_f32_e32 v193, v193
	v_rcp_f32_e32 v194, v194
	v_rcp_f32_e32 v195, v195
	v_rcp_f32_e32 v196, v196
	v_rcp_f32_e32 v197, v197
	v_rcp_f32_e32 v198, v198
	v_rcp_f32_e32 v199, v199
	v_pk_mul_f32 v[92:93], v[92:93], v[192:193]
	v_pk_mul_f32 v[94:95], v[94:95], v[194:195]
	v_pk_mul_f32 v[88:89], v[88:89], v[196:197]
	v_pk_mul_f32 v[90:91], v[90:91], v[198:199]
	v_pk_mul_f32 v[92:93], v[84:85], v[92:93]
	v_pk_mul_f32 v[94:95], v[86:87], v[94:95]
	v_pk_mul_f32 v[88:89], v[80:81], v[88:89]
	v_pk_mul_f32 v[90:91], v[82:83], v[90:91]
	v_cvt_pk_bf16_f32 v208, v92, v93
	v_cvt_pk_bf16_f32 v209, v94, v95
	v_cvt_pk_bf16_f32 v210, v88, v89
	v_cvt_pk_bf16_f32 v211, v90, v91
	s_mov_b64 s[100:101], 0x2c000
	v_lshl_add_u64 v[216:217], v[232:233], 0, s[100:101]
	global_store_dwordx4 v[216:217], v[208:211], off
	s_waitcnt lgkmcnt(4)
	v_pk_mul_f32 v[76:77], v[76:77], v[178:179] op_sel_hi:[1,0]
	v_pk_mul_f32 v[78:79], v[78:79], v[178:179] op_sel_hi:[1,0]
	v_pk_mul_f32 v[72:73], v[72:73], v[178:179] op_sel_hi:[1,0]
	v_pk_mul_f32 v[74:75], v[74:75], v[178:179] op_sel_hi:[1,0]
	v_pk_mul_f32 v[68:69], v[68:69], v[178:179] op_sel_hi:[1,0]
	v_pk_mul_f32 v[70:71], v[70:71], v[178:179] op_sel_hi:[1,0]
	v_pk_mul_f32 v[64:65], v[64:65], v[178:179] op_sel_hi:[1,0]
	v_pk_mul_f32 v[66:67], v[66:67], v[178:179] op_sel_hi:[1,0]
	v_pk_mul_f32 v[200:201], v[76:77], v[188:189] op_sel_hi:[1,0]
	v_pk_mul_f32 v[202:203], v[78:79], v[188:189] op_sel_hi:[1,0]
	v_pk_mul_f32 v[204:205], v[72:73], v[188:189] op_sel_hi:[1,0]
	v_pk_mul_f32 v[206:207], v[74:75], v[188:189] op_sel_hi:[1,0]
	v_exp_f32_e32 v200, v200
	v_exp_f32_e32 v201, v201
	v_exp_f32_e32 v202, v202
	v_exp_f32_e32 v203, v203
	v_exp_f32_e32 v204, v204
	v_exp_f32_e32 v205, v205
	v_exp_f32_e32 v206, v206
	v_exp_f32_e32 v207, v207
	v_add_f32_e32 v200, 1.0, v200
	v_add_f32_e32 v201, 1.0, v201
	v_add_f32_e32 v202, 1.0, v202
	v_add_f32_e32 v203, 1.0, v203
	v_add_f32_e32 v204, 1.0, v204
	v_add_f32_e32 v205, 1.0, v205
	v_add_f32_e32 v206, 1.0, v206
	v_add_f32_e32 v207, 1.0, v207
	v_rcp_f32_e32 v200, v200
	v_rcp_f32_e32 v201, v201
	v_rcp_f32_e32 v202, v202
	v_rcp_f32_e32 v203, v203
	v_rcp_f32_e32 v204, v204
	v_rcp_f32_e32 v205, v205
	v_rcp_f32_e32 v206, v206
	v_rcp_f32_e32 v207, v207
	v_pk_mul_f32 v[76:77], v[76:77], v[200:201]
	v_pk_mul_f32 v[78:79], v[78:79], v[202:203]
	v_pk_mul_f32 v[72:73], v[72:73], v[204:205]
	v_pk_mul_f32 v[74:75], v[74:75], v[206:207]
	v_pk_mul_f32 v[76:77], v[68:69], v[76:77]
	v_pk_mul_f32 v[78:79], v[70:71], v[78:79]
	v_pk_mul_f32 v[72:73], v[64:65], v[72:73]
	v_pk_mul_f32 v[74:75], v[66:67], v[74:75]
	v_cvt_pk_bf16_f32 v212, v76, v77
	v_cvt_pk_bf16_f32 v213, v78, v79
	v_cvt_pk_bf16_f32 v214, v72, v73
	v_cvt_pk_bf16_f32 v215, v74, v75
	s_mov_b64 s[100:101], 0x42000
	v_lshl_add_u64 v[216:217], v[232:233], 0, s[100:101]
	global_store_dwordx4 v[216:217], v[212:215], off
	s_waitcnt lgkmcnt(3)
	v_pk_mul_f32 v[60:61], v[60:61], v[180:181] op_sel_hi:[1,0]
	v_pk_mul_f32 v[62:63], v[62:63], v[180:181] op_sel_hi:[1,0]
	v_pk_mul_f32 v[56:57], v[56:57], v[180:181] op_sel_hi:[1,0]
	v_pk_mul_f32 v[58:59], v[58:59], v[180:181] op_sel_hi:[1,0]
	v_pk_mul_f32 v[52:53], v[52:53], v[180:181] op_sel_hi:[1,0]
	v_pk_mul_f32 v[54:55], v[54:55], v[180:181] op_sel_hi:[1,0]
	v_pk_mul_f32 v[48:49], v[48:49], v[180:181] op_sel_hi:[1,0]
	v_pk_mul_f32 v[50:51], v[50:51], v[180:181] op_sel_hi:[1,0]
	v_pk_mul_f32 v[192:193], v[60:61], v[188:189] op_sel_hi:[1,0]
	v_pk_mul_f32 v[194:195], v[62:63], v[188:189] op_sel_hi:[1,0]
	v_pk_mul_f32 v[196:197], v[56:57], v[188:189] op_sel_hi:[1,0]
	v_pk_mul_f32 v[198:199], v[58:59], v[188:189] op_sel_hi:[1,0]
	v_exp_f32_e32 v192, v192
	v_exp_f32_e32 v193, v193
	v_exp_f32_e32 v194, v194
	v_exp_f32_e32 v195, v195
	v_exp_f32_e32 v196, v196
	v_exp_f32_e32 v197, v197
	v_exp_f32_e32 v198, v198
	v_exp_f32_e32 v199, v199
	v_add_f32_e32 v192, 1.0, v192
	v_add_f32_e32 v193, 1.0, v193
	v_add_f32_e32 v194, 1.0, v194
	v_add_f32_e32 v195, 1.0, v195
	v_add_f32_e32 v196, 1.0, v196
	v_add_f32_e32 v197, 1.0, v197
	v_add_f32_e32 v198, 1.0, v198
	v_add_f32_e32 v199, 1.0, v199
	v_rcp_f32_e32 v192, v192
	v_rcp_f32_e32 v193, v193
	v_rcp_f32_e32 v194, v194
	v_rcp_f32_e32 v195, v195
	v_rcp_f32_e32 v196, v196
	v_rcp_f32_e32 v197, v197
	v_rcp_f32_e32 v198, v198
	v_rcp_f32_e32 v199, v199
	v_pk_mul_f32 v[60:61], v[60:61], v[192:193]
	v_pk_mul_f32 v[62:63], v[62:63], v[194:195]
	v_pk_mul_f32 v[56:57], v[56:57], v[196:197]
	v_pk_mul_f32 v[58:59], v[58:59], v[198:199]
	v_pk_mul_f32 v[60:61], v[52:53], v[60:61]
	v_pk_mul_f32 v[62:63], v[54:55], v[62:63]
	v_pk_mul_f32 v[56:57], v[48:49], v[56:57]
	v_pk_mul_f32 v[58:59], v[50:51], v[58:59]
	v_cvt_pk_bf16_f32 v208, v60, v61
	v_cvt_pk_bf16_f32 v209, v62, v63
	v_cvt_pk_bf16_f32 v210, v56, v57
	v_cvt_pk_bf16_f32 v211, v58, v59
	s_mov_b64 s[100:101], 0xb0000
	v_lshl_add_u64 v[216:217], v[232:233], 0, s[100:101]
	global_store_dwordx4 v[216:217], v[208:211], off
	s_waitcnt lgkmcnt(2)
	v_pk_mul_f32 v[44:45], v[44:45], v[182:183] op_sel_hi:[1,0]
	v_pk_mul_f32 v[46:47], v[46:47], v[182:183] op_sel_hi:[1,0]
	v_pk_mul_f32 v[40:41], v[40:41], v[182:183] op_sel_hi:[1,0]
	v_pk_mul_f32 v[42:43], v[42:43], v[182:183] op_sel_hi:[1,0]
	v_pk_mul_f32 v[36:37], v[36:37], v[182:183] op_sel_hi:[1,0]
	v_pk_mul_f32 v[38:39], v[38:39], v[182:183] op_sel_hi:[1,0]
	v_pk_mul_f32 v[32:33], v[32:33], v[182:183] op_sel_hi:[1,0]
	v_pk_mul_f32 v[34:35], v[34:35], v[182:183] op_sel_hi:[1,0]
	v_pk_mul_f32 v[200:201], v[44:45], v[188:189] op_sel_hi:[1,0]
	v_pk_mul_f32 v[202:203], v[46:47], v[188:189] op_sel_hi:[1,0]
	v_pk_mul_f32 v[204:205], v[40:41], v[188:189] op_sel_hi:[1,0]
	v_pk_mul_f32 v[206:207], v[42:43], v[188:189] op_sel_hi:[1,0]
	v_exp_f32_e32 v200, v200
	v_exp_f32_e32 v201, v201
	v_exp_f32_e32 v202, v202
	v_exp_f32_e32 v203, v203
	v_exp_f32_e32 v204, v204
	v_exp_f32_e32 v205, v205
	v_exp_f32_e32 v206, v206
	v_exp_f32_e32 v207, v207
	v_add_f32_e32 v200, 1.0, v200
	v_add_f32_e32 v201, 1.0, v201
	v_add_f32_e32 v202, 1.0, v202
	v_add_f32_e32 v203, 1.0, v203
	v_add_f32_e32 v204, 1.0, v204
	v_add_f32_e32 v205, 1.0, v205
	v_add_f32_e32 v206, 1.0, v206
	v_add_f32_e32 v207, 1.0, v207
	v_rcp_f32_e32 v200, v200
	v_rcp_f32_e32 v201, v201
	v_rcp_f32_e32 v202, v202
	v_rcp_f32_e32 v203, v203
	v_rcp_f32_e32 v204, v204
	v_rcp_f32_e32 v205, v205
	v_rcp_f32_e32 v206, v206
	v_rcp_f32_e32 v207, v207
	v_pk_mul_f32 v[44:45], v[44:45], v[200:201]
	v_pk_mul_f32 v[46:47], v[46:47], v[202:203]
	v_pk_mul_f32 v[40:41], v[40:41], v[204:205]
	v_pk_mul_f32 v[42:43], v[42:43], v[206:207]
	v_pk_mul_f32 v[44:45], v[36:37], v[44:45]
	v_pk_mul_f32 v[46:47], v[38:39], v[46:47]
	v_pk_mul_f32 v[40:41], v[32:33], v[40:41]
	v_pk_mul_f32 v[42:43], v[34:35], v[42:43]
	v_cvt_pk_bf16_f32 v212, v44, v45
	v_cvt_pk_bf16_f32 v213, v46, v47
	v_cvt_pk_bf16_f32 v214, v40, v41
	v_cvt_pk_bf16_f32 v215, v42, v43
	s_mov_b64 s[100:101], 0xc6000
	v_lshl_add_u64 v[216:217], v[232:233], 0, s[100:101]
	global_store_dwordx4 v[216:217], v[212:215], off
	s_waitcnt lgkmcnt(1)
	v_pk_mul_f32 v[28:29], v[28:29], v[184:185] op_sel_hi:[1,0]
	v_pk_mul_f32 v[30:31], v[30:31], v[184:185] op_sel_hi:[1,0]
	v_pk_mul_f32 v[24:25], v[24:25], v[184:185] op_sel_hi:[1,0]
	v_pk_mul_f32 v[26:27], v[26:27], v[184:185] op_sel_hi:[1,0]
	v_pk_mul_f32 v[20:21], v[20:21], v[184:185] op_sel_hi:[1,0]
	v_pk_mul_f32 v[22:23], v[22:23], v[184:185] op_sel_hi:[1,0]
	v_pk_mul_f32 v[16:17], v[16:17], v[184:185] op_sel_hi:[1,0]
	v_pk_mul_f32 v[18:19], v[18:19], v[184:185] op_sel_hi:[1,0]
	v_pk_mul_f32 v[192:193], v[28:29], v[188:189] op_sel_hi:[1,0]
	v_pk_mul_f32 v[194:195], v[30:31], v[188:189] op_sel_hi:[1,0]
	v_pk_mul_f32 v[196:197], v[24:25], v[188:189] op_sel_hi:[1,0]
	v_pk_mul_f32 v[198:199], v[26:27], v[188:189] op_sel_hi:[1,0]
	v_exp_f32_e32 v192, v192
	v_exp_f32_e32 v193, v193
	v_exp_f32_e32 v194, v194
	v_exp_f32_e32 v195, v195
	v_exp_f32_e32 v196, v196
	v_exp_f32_e32 v197, v197
	v_exp_f32_e32 v198, v198
	v_exp_f32_e32 v199, v199
	v_add_f32_e32 v192, 1.0, v192
	v_add_f32_e32 v193, 1.0, v193
	v_add_f32_e32 v194, 1.0, v194
	v_add_f32_e32 v195, 1.0, v195
	v_add_f32_e32 v196, 1.0, v196
	v_add_f32_e32 v197, 1.0, v197
	v_add_f32_e32 v198, 1.0, v198
	v_add_f32_e32 v199, 1.0, v199
	v_rcp_f32_e32 v192, v192
	v_rcp_f32_e32 v193, v193
	v_rcp_f32_e32 v194, v194
	v_rcp_f32_e32 v195, v195
	v_rcp_f32_e32 v196, v196
	v_rcp_f32_e32 v197, v197
	v_rcp_f32_e32 v198, v198
	v_rcp_f32_e32 v199, v199
	v_pk_mul_f32 v[28:29], v[28:29], v[192:193]
	v_pk_mul_f32 v[30:31], v[30:31], v[194:195]
	v_pk_mul_f32 v[24:25], v[24:25], v[196:197]
	v_pk_mul_f32 v[26:27], v[26:27], v[198:199]
	v_pk_mul_f32 v[28:29], v[20:21], v[28:29]
	v_pk_mul_f32 v[30:31], v[22:23], v[30:31]
	v_pk_mul_f32 v[24:25], v[16:17], v[24:25]
	v_pk_mul_f32 v[26:27], v[18:19], v[26:27]
	v_cvt_pk_bf16_f32 v208, v28, v29
	v_cvt_pk_bf16_f32 v209, v30, v31
	v_cvt_pk_bf16_f32 v210, v24, v25
	v_cvt_pk_bf16_f32 v211, v26, v27
	s_mov_b64 s[100:101], 0xdc000
	v_lshl_add_u64 v[216:217], v[232:233], 0, s[100:101]
	global_store_dwordx4 v[216:217], v[208:211], off
	s_waitcnt lgkmcnt(0)
	v_pk_mul_f32 v[12:13], v[12:13], v[186:187] op_sel_hi:[1,0]
	v_pk_mul_f32 v[14:15], v[14:15], v[186:187] op_sel_hi:[1,0]
	v_pk_mul_f32 v[8:9], v[8:9], v[186:187] op_sel_hi:[1,0]
	v_pk_mul_f32 v[10:11], v[10:11], v[186:187] op_sel_hi:[1,0]
	v_pk_mul_f32 v[4:5], v[4:5], v[186:187] op_sel_hi:[1,0]
	v_pk_mul_f32 v[6:7], v[6:7], v[186:187] op_sel_hi:[1,0]
	v_pk_mul_f32 v[0:1], v[0:1], v[186:187] op_sel_hi:[1,0]
	v_pk_mul_f32 v[2:3], v[2:3], v[186:187] op_sel_hi:[1,0]
	v_pk_mul_f32 v[200:201], v[12:13], v[188:189] op_sel_hi:[1,0]
	v_pk_mul_f32 v[202:203], v[14:15], v[188:189] op_sel_hi:[1,0]
	v_pk_mul_f32 v[204:205], v[8:9], v[188:189] op_sel_hi:[1,0]
	v_pk_mul_f32 v[206:207], v[10:11], v[188:189] op_sel_hi:[1,0]
	v_exp_f32_e32 v200, v200
	v_exp_f32_e32 v201, v201
	v_exp_f32_e32 v202, v202
	v_exp_f32_e32 v203, v203
	v_exp_f32_e32 v204, v204
	v_exp_f32_e32 v205, v205
	v_exp_f32_e32 v206, v206
	v_exp_f32_e32 v207, v207
	v_add_f32_e32 v200, 1.0, v200
	v_add_f32_e32 v201, 1.0, v201
	v_add_f32_e32 v202, 1.0, v202
	v_add_f32_e32 v203, 1.0, v203
	v_add_f32_e32 v204, 1.0, v204
	v_add_f32_e32 v205, 1.0, v205
	v_add_f32_e32 v206, 1.0, v206
	v_add_f32_e32 v207, 1.0, v207
	v_rcp_f32_e32 v200, v200
	v_rcp_f32_e32 v201, v201
	v_rcp_f32_e32 v202, v202
	v_rcp_f32_e32 v203, v203
	v_rcp_f32_e32 v204, v204
	v_rcp_f32_e32 v205, v205
	v_rcp_f32_e32 v206, v206
	v_rcp_f32_e32 v207, v207
	v_pk_mul_f32 v[12:13], v[12:13], v[200:201]
	v_pk_mul_f32 v[14:15], v[14:15], v[202:203]
	v_pk_mul_f32 v[8:9], v[8:9], v[204:205]
	v_pk_mul_f32 v[10:11], v[10:11], v[206:207]
	v_pk_mul_f32 v[12:13], v[4:5], v[12:13]
	v_pk_mul_f32 v[14:15], v[6:7], v[14:15]
	v_pk_mul_f32 v[8:9], v[0:1], v[8:9]
	v_pk_mul_f32 v[10:11], v[2:3], v[10:11]
	v_cvt_pk_bf16_f32 v212, v12, v13
	v_cvt_pk_bf16_f32 v213, v14, v15
	v_cvt_pk_bf16_f32 v214, v8, v9
	v_cvt_pk_bf16_f32 v215, v10, v11
	s_mov_b64 s[100:101], 0xf2000
	v_lshl_add_u64 v[216:217], v[232:233], 0, s[100:101]
	global_store_dwordx4 v[216:217], v[212:215], off
	s_andn2_b64 vcc, exec, s[4:5]
	s_mov_b64 s[4:5], -1
	s_cbranch_vccnz .LBB0_472
	s_andn2_b64 vcc, exec, s[0:1]
	s_cbranch_vccnz .LBB0_471
	s_nop 0
	s_branch .LBB0_471

.LBB0_1062:
	v_lshl_add_u32 v160, s12, 10, v153
	v_lshl_or_b32 v150, s13, 7, v154
	v_lshl_add_u32 v159, s30, 8, v131
	v_ashrrev_i32_e32 v151, 31, v150
	v_mov_b64_e32 v[148:149], s[16:17]
	v_mad_i64_i32 v[164:165], s[12:13], v159, s59, v[148:149]
	v_lshlrev_b64 v[150:151], 1, v[150:151]
	v_lshl_add_u64 v[164:165], v[164:165], 0, v[150:151]
	v_mov_b32_e32 v232, v164
	v_mov_b32_e32 v233, v165
	ds_read_b32 v172, v160
	ds_read_b32 v174, v160 offset:64
	ds_read_b32 v176, v160 offset:128
	ds_read_b32 v178, v160 offset:192
	ds_read_b32 v180, v160 offset:512
	ds_read_b32 v182, v160 offset:576
	ds_read_b32 v184, v160 offset:640
	ds_read_b32 v186, v160 offset:704
	v_mov_b32_e32 v188, 0xbfb8aa3b
	s_waitcnt lgkmcnt(7)
	v_pk_mul_f32 v[124:125], v[124:125], v[172:173] op_sel_hi:[1,0]
	v_pk_mul_f32 v[126:127], v[126:127], v[172:173] op_sel_hi:[1,0]
	v_pk_mul_f32 v[120:121], v[120:121], v[172:173] op_sel_hi:[1,0]
	v_pk_mul_f32 v[122:123], v[122:123], v[172:173] op_sel_hi:[1,0]
	v_pk_mul_f32 v[116:117], v[116:117], v[172:173] op_sel_hi:[1,0]
	v_pk_mul_f32 v[118:119], v[118:119], v[172:173] op_sel_hi:[1,0]
	v_pk_mul_f32 v[112:113], v[112:113], v[172:173] op_sel_hi:[1,0]
	v_pk_mul_f32 v[114:115], v[114:115], v[172:173] op_sel_hi:[1,0]
	v_pk_mul_f32 v[192:193], v[124:125], v[188:189] op_sel_hi:[1,0]
	v_pk_mul_f32 v[194:195], v[126:127], v[188:189] op_sel_hi:[1,0]
	v_pk_mul_f32 v[196:197], v[120:121], v[188:189] op_sel_hi:[1,0]
	v_pk_mul_f32 v[198:199], v[122:123], v[188:189] op_sel_hi:[1,0]
	v_exp_f32_e32 v192, v192
	v_exp_f32_e32 v193, v193
	v_exp_f32_e32 v194, v194
	v_exp_f32_e32 v195, v195
	v_exp_f32_e32 v196, v196
	v_exp_f32_e32 v197, v197
	v_exp_f32_e32 v198, v198
	v_exp_f32_e32 v199, v199
	v_add_f32_e32 v192, 1.0, v192
	v_add_f32_e32 v193, 1.0, v193
	v_add_f32_e32 v194, 1.0, v194
	v_add_f32_e32 v195, 1.0, v195
	v_add_f32_e32 v196, 1.0, v196
	v_add_f32_e32 v197, 1.0, v197
	v_add_f32_e32 v198, 1.0, v198
	v_add_f32_e32 v199, 1.0, v199
	v_rcp_f32_e32 v192, v192
	v_rcp_f32_e32 v193, v193
	v_rcp_f32_e32 v194, v194
	v_rcp_f32_e32 v195, v195
	v_rcp_f32_e32 v196, v196
	v_rcp_f32_e32 v197, v197
	v_rcp_f32_e32 v198, v198
	v_rcp_f32_e32 v199, v199
	v_pk_mul_f32 v[124:125], v[124:125], v[192:193]
	v_pk_mul_f32 v[126:127], v[126:127], v[194:195]
	v_pk_mul_f32 v[120:121], v[120:121], v[196:197]
	v_pk_mul_f32 v[122:123], v[122:123], v[198:199]
	v_pk_mul_f32 v[124:125], v[116:117], v[124:125]
	v_pk_mul_f32 v[126:127], v[118:119], v[126:127]
	v_pk_mul_f32 v[120:121], v[112:113], v[120:121]
	v_pk_mul_f32 v[122:123], v[114:115], v[122:123]
	v_cvt_pk_bf16_f32 v208, v124, v125
	v_cvt_pk_bf16_f32 v209, v126, v127
	v_cvt_pk_bf16_f32 v210, v120, v121
	v_cvt_pk_bf16_f32 v211, v122, v123
	global_store_dwordx4 v[232:233], v[208:211], off
	s_waitcnt lgkmcnt(6)
	v_pk_mul_f32 v[108:109], v[108:109], v[174:175] op_sel_hi:[1,0]
	v_pk_mul_f32 v[110:111], v[110:111], v[174:175] op_sel_hi:[1,0]
	v_pk_mul_f32 v[104:105], v[104:105], v[174:175] op_sel_hi:[1,0]
	v_pk_mul_f32 v[106:107], v[106:107], v[174:175] op_sel_hi:[1,0]
	v_pk_mul_f32 v[100:101], v[100:101], v[174:175] op_sel_hi:[1,0]
	v_pk_mul_f32 v[102:103], v[102:103], v[174:175] op_sel_hi:[1,0]
	v_pk_mul_f32 v[96:97], v[96:97], v[174:175] op_sel_hi:[1,0]
	v_pk_mul_f32 v[98:99], v[98:99], v[174:175] op_sel_hi:[1,0]
	v_pk_mul_f32 v[200:201], v[108:109], v[188:189] op_sel_hi:[1,0]
	v_pk_mul_f32 v[202:203], v[110:111], v[188:189] op_sel_hi:[1,0]
	v_pk_mul_f32 v[204:205], v[104:105], v[188:189] op_sel_hi:[1,0]
	v_pk_mul_f32 v[206:207], v[106:107], v[188:189] op_sel_hi:[1,0]
	v_exp_f32_e32 v200, v200
	v_exp_f32_e32 v201, v201
	v_exp_f32_e32 v202, v202
	v_exp_f32_e32 v203, v203
	v_exp_f32_e32 v204, v204
	v_exp_f32_e32 v205, v205
	v_exp_f32_e32 v206, v206
	v_exp_f32_e32 v207, v207
	v_add_f32_e32 v200, 1.0, v200
	v_add_f32_e32 v201, 1.0, v201
	v_add_f32_e32 v202, 1.0, v202
	v_add_f32_e32 v203, 1.0, v203
	v_add_f32_e32 v204, 1.0, v204
	v_add_f32_e32 v205, 1.0, v205
	v_add_f32_e32 v206, 1.0, v206
	v_add_f32_e32 v207, 1.0, v207
	v_rcp_f32_e32 v200, v200
	v_rcp_f32_e32 v201, v201
	v_rcp_f32_e32 v202, v202
	v_rcp_f32_e32 v203, v203
	v_rcp_f32_e32 v204, v204
	v_rcp_f32_e32 v205, v205
	v_rcp_f32_e32 v206, v206
	v_rcp_f32_e32 v207, v207
	v_pk_mul_f32 v[108:109], v[108:109], v[200:201]
	v_pk_mul_f32 v[110:111], v[110:111], v[202:203]
	v_pk_mul_f32 v[104:105], v[104:105], v[204:205]
	v_pk_mul_f32 v[106:107], v[106:107], v[206:207]
	v_pk_mul_f32 v[108:109], v[100:101], v[108:109]
	v_pk_mul_f32 v[110:111], v[102:103], v[110:111]
	v_pk_mul_f32 v[104:105], v[96:97], v[104:105]
	v_pk_mul_f32 v[106:107], v[98:99], v[106:107]
	v_cvt_pk_bf16_f32 v212, v108, v109
	v_cvt_pk_bf16_f32 v213, v110, v111
	v_cvt_pk_bf16_f32 v214, v104, v105
	v_cvt_pk_bf16_f32 v215, v106, v107
	s_mov_b64 s[100:101], 0x16000
	v_lshl_add_u64 v[216:217], v[232:233], 0, s[100:101]
	global_store_dwordx4 v[216:217], v[212:215], off
	s_waitcnt lgkmcnt(5)
	v_pk_mul_f32 v[92:93], v[92:93], v[176:177] op_sel_hi:[1,0]
	v_pk_mul_f32 v[94:95], v[94:95], v[176:177] op_sel_hi:[1,0]
	v_pk_mul_f32 v[88:89], v[88:89], v[176:177] op_sel_hi:[1,0]
	v_pk_mul_f32 v[90:91], v[90:91], v[176:177] op_sel_hi:[1,0]
	v_pk_mul_f32 v[84:85], v[84:85], v[176:177] op_sel_hi:[1,0]
	v_pk_mul_f32 v[86:87], v[86:87], v[176:177] op_sel_hi:[1,0]
	v_pk_mul_f32 v[80:81], v[80:81], v[176:177] op_sel_hi:[1,0]
	v_pk_mul_f32 v[82:83], v[82:83], v[176:177] op_sel_hi:[1,0]
	v_pk_mul_f32 v[192:193], v[92:93], v[188:189] op_sel_hi:[1,0]
	v_pk_mul_f32 v[194:195], v[94:95], v[188:189] op_sel_hi:[1,0]
	v_pk_mul_f32 v[196:197], v[88:89], v[188:189] op_sel_hi:[1,0]
	v_pk_mul_f32 v[198:199], v[90:91], v[188:189] op_sel_hi:[1,0]
	v_exp_f32_e32 v192, v192
	v_exp_f32_e32 v193, v193
	v_exp_f32_e32 v194, v194
	v_exp_f32_e32 v195, v195
	v_exp_f32_e32 v196, v196
	v_exp_f32_e32 v197, v197
	v_exp_f32_e32 v198, v198
	v_exp_f32_e32 v199, v199
	v_add_f32_e32 v192, 1.0, v192
	v_add_f32_e32 v193, 1.0, v193
	v_add_f32_e32 v194, 1.0, v194
	v_add_f32_e32 v195, 1.0, v195
	v_add_f32_e32 v196, 1.0, v196
	v_add_f32_e32 v197, 1.0, v197
	v_add_f32_e32 v198, 1.0, v198
	v_add_f32_e32 v199, 1.0, v199
	v_rcp_f32_e32 v192, v192
	v_rcp_f32_e32 v193, v193
	v_rcp_f32_e32 v194, v194
	v_rcp_f32_e32 v195, v195
	v_rcp_f32_e32 v196, v196
	v_rcp_f32_e32 v197, v197
	v_rcp_f32_e32 v198, v198
	v_rcp_f32_e32 v199, v199
	v_pk_mul_f32 v[92:93], v[92:93], v[192:193]
	v_pk_mul_f32 v[94:95], v[94:95], v[194:195]
	v_pk_mul_f32 v[88:89], v[88:89], v[196:197]
	v_pk_mul_f32 v[90:91], v[90:91], v[198:199]
	v_pk_mul_f32 v[92:93], v[84:85], v[92:93]
	v_pk_mul_f32 v[94:95], v[86:87], v[94:95]
	v_pk_mul_f32 v[88:89], v[80:81], v[88:89]
	v_pk_mul_f32 v[90:91], v[82:83], v[90:91]
	v_cvt_pk_bf16_f32 v208, v92, v93
	v_cvt_pk_bf16_f32 v209, v94, v95
	v_cvt_pk_bf16_f32 v210, v88, v89
	v_cvt_pk_bf16_f32 v211, v90, v91
	s_mov_b64 s[100:101], 0x2c000
	v_lshl_add_u64 v[216:217], v[232:233], 0, s[100:101]
	global_store_dwordx4 v[216:217], v[208:211], off
	s_waitcnt lgkmcnt(4)
	v_pk_mul_f32 v[76:77], v[76:77], v[178:179] op_sel_hi:[1,0]
	v_pk_mul_f32 v[78:79], v[78:79], v[178:179] op_sel_hi:[1,0]
	v_pk_mul_f32 v[72:73], v[72:73], v[178:179] op_sel_hi:[1,0]
	v_pk_mul_f32 v[74:75], v[74:75], v[178:179] op_sel_hi:[1,0]
	v_pk_mul_f32 v[68:69], v[68:69], v[178:179] op_sel_hi:[1,0]
	v_pk_mul_f32 v[70:71], v[70:71], v[178:179] op_sel_hi:[1,0]
	v_pk_mul_f32 v[64:65], v[64:65], v[178:179] op_sel_hi:[1,0]
	v_pk_mul_f32 v[66:67], v[66:67], v[178:179] op_sel_hi:[1,0]
	v_pk_mul_f32 v[200:201], v[76:77], v[188:189] op_sel_hi:[1,0]
	v_pk_mul_f32 v[202:203], v[78:79], v[188:189] op_sel_hi:[1,0]
	v_pk_mul_f32 v[204:205], v[72:73], v[188:189] op_sel_hi:[1,0]
	v_pk_mul_f32 v[206:207], v[74:75], v[188:189] op_sel_hi:[1,0]
	v_exp_f32_e32 v200, v200
	v_exp_f32_e32 v201, v201
	v_exp_f32_e32 v202, v202
	v_exp_f32_e32 v203, v203
	v_exp_f32_e32 v204, v204
	v_exp_f32_e32 v205, v205
	v_exp_f32_e32 v206, v206
	v_exp_f32_e32 v207, v207
	v_add_f32_e32 v200, 1.0, v200
	v_add_f32_e32 v201, 1.0, v201
	v_add_f32_e32 v202, 1.0, v202
	v_add_f32_e32 v203, 1.0, v203
	v_add_f32_e32 v204, 1.0, v204
	v_add_f32_e32 v205, 1.0, v205
	v_add_f32_e32 v206, 1.0, v206
	v_add_f32_e32 v207, 1.0, v207
	v_rcp_f32_e32 v200, v200
	v_rcp_f32_e32 v201, v201
	v_rcp_f32_e32 v202, v202
	v_rcp_f32_e32 v203, v203
	v_rcp_f32_e32 v204, v204
	v_rcp_f32_e32 v205, v205
	v_rcp_f32_e32 v206, v206
	v_rcp_f32_e32 v207, v207
	v_pk_mul_f32 v[76:77], v[76:77], v[200:201]
	v_pk_mul_f32 v[78:79], v[78:79], v[202:203]
	v_pk_mul_f32 v[72:73], v[72:73], v[204:205]
	v_pk_mul_f32 v[74:75], v[74:75], v[206:207]
	v_pk_mul_f32 v[76:77], v[68:69], v[76:77]
	v_pk_mul_f32 v[78:79], v[70:71], v[78:79]
	v_pk_mul_f32 v[72:73], v[64:65], v[72:73]
	v_pk_mul_f32 v[74:75], v[66:67], v[74:75]
	v_cvt_pk_bf16_f32 v212, v76, v77
	v_cvt_pk_bf16_f32 v213, v78, v79
	v_cvt_pk_bf16_f32 v214, v72, v73
	v_cvt_pk_bf16_f32 v215, v74, v75
	s_mov_b64 s[100:101], 0x42000
	v_lshl_add_u64 v[216:217], v[232:233], 0, s[100:101]
	global_store_dwordx4 v[216:217], v[212:215], off
	s_waitcnt lgkmcnt(3)
	v_pk_mul_f32 v[60:61], v[60:61], v[180:181] op_sel_hi:[1,0]
	v_pk_mul_f32 v[62:63], v[62:63], v[180:181] op_sel_hi:[1,0]
	v_pk_mul_f32 v[56:57], v[56:57], v[180:181] op_sel_hi:[1,0]
	v_pk_mul_f32 v[58:59], v[58:59], v[180:181] op_sel_hi:[1,0]
	v_pk_mul_f32 v[52:53], v[52:53], v[180:181] op_sel_hi:[1,0]
	v_pk_mul_f32 v[54:55], v[54:55], v[180:181] op_sel_hi:[1,0]
	v_pk_mul_f32 v[48:49], v[48:49], v[180:181] op_sel_hi:[1,0]
	v_pk_mul_f32 v[50:51], v[50:51], v[180:181] op_sel_hi:[1,0]
	v_pk_mul_f32 v[192:193], v[60:61], v[188:189] op_sel_hi:[1,0]
	v_pk_mul_f32 v[194:195], v[62:63], v[188:189] op_sel_hi:[1,0]
	v_pk_mul_f32 v[196:197], v[56:57], v[188:189] op_sel_hi:[1,0]
	v_pk_mul_f32 v[198:199], v[58:59], v[188:189] op_sel_hi:[1,0]
	v_exp_f32_e32 v192, v192
	v_exp_f32_e32 v193, v193
	v_exp_f32_e32 v194, v194
	v_exp_f32_e32 v195, v195
	v_exp_f32_e32 v196, v196
	v_exp_f32_e32 v197, v197
	v_exp_f32_e32 v198, v198
	v_exp_f32_e32 v199, v199
	v_add_f32_e32 v192, 1.0, v192
	v_add_f32_e32 v193, 1.0, v193
	v_add_f32_e32 v194, 1.0, v194
	v_add_f32_e32 v195, 1.0, v195
	v_add_f32_e32 v196, 1.0, v196
	v_add_f32_e32 v197, 1.0, v197
	v_add_f32_e32 v198, 1.0, v198
	v_add_f32_e32 v199, 1.0, v199
	v_rcp_f32_e32 v192, v192
	v_rcp_f32_e32 v193, v193
	v_rcp_f32_e32 v194, v194
	v_rcp_f32_e32 v195, v195
	v_rcp_f32_e32 v196, v196
	v_rcp_f32_e32 v197, v197
	v_rcp_f32_e32 v198, v198
	v_rcp_f32_e32 v199, v199
	v_pk_mul_f32 v[60:61], v[60:61], v[192:193]
	v_pk_mul_f32 v[62:63], v[62:63], v[194:195]
	v_pk_mul_f32 v[56:57], v[56:57], v[196:197]
	v_pk_mul_f32 v[58:59], v[58:59], v[198:199]
	v_pk_mul_f32 v[60:61], v[52:53], v[60:61]
	v_pk_mul_f32 v[62:63], v[54:55], v[62:63]
	v_pk_mul_f32 v[56:57], v[48:49], v[56:57]
	v_pk_mul_f32 v[58:59], v[50:51], v[58:59]
	v_cvt_pk_bf16_f32 v208, v60, v61
	v_cvt_pk_bf16_f32 v209, v62, v63
	v_cvt_pk_bf16_f32 v210, v56, v57
	v_cvt_pk_bf16_f32 v211, v58, v59
	s_mov_b64 s[100:101], 0xb0000
	v_lshl_add_u64 v[216:217], v[232:233], 0, s[100:101]
	global_store_dwordx4 v[216:217], v[208:211], off
	s_waitcnt lgkmcnt(2)
	v_pk_mul_f32 v[44:45], v[44:45], v[182:183] op_sel_hi:[1,0]
	v_pk_mul_f32 v[46:47], v[46:47], v[182:183] op_sel_hi:[1,0]
	v_pk_mul_f32 v[40:41], v[40:41], v[182:183] op_sel_hi:[1,0]
	v_pk_mul_f32 v[42:43], v[42:43], v[182:183] op_sel_hi:[1,0]
	v_pk_mul_f32 v[36:37], v[36:37], v[182:183] op_sel_hi:[1,0]
	v_pk_mul_f32 v[38:39], v[38:39], v[182:183] op_sel_hi:[1,0]
	v_pk_mul_f32 v[32:33], v[32:33], v[182:183] op_sel_hi:[1,0]
	v_pk_mul_f32 v[34:35], v[34:35], v[182:183] op_sel_hi:[1,0]
	v_pk_mul_f32 v[200:201], v[44:45], v[188:189] op_sel_hi:[1,0]
	v_pk_mul_f32 v[202:203], v[46:47], v[188:189] op_sel_hi:[1,0]
	v_pk_mul_f32 v[204:205], v[40:41], v[188:189] op_sel_hi:[1,0]
	v_pk_mul_f32 v[206:207], v[42:43], v[188:189] op_sel_hi:[1,0]
	v_exp_f32_e32 v200, v200
	v_exp_f32_e32 v201, v201
	v_exp_f32_e32 v202, v202
	v_exp_f32_e32 v203, v203
	v_exp_f32_e32 v204, v204
	v_exp_f32_e32 v205, v205
	v_exp_f32_e32 v206, v206
	v_exp_f32_e32 v207, v207
	v_add_f32_e32 v200, 1.0, v200
	v_add_f32_e32 v201, 1.0, v201
	v_add_f32_e32 v202, 1.0, v202
	v_add_f32_e32 v203, 1.0, v203
	v_add_f32_e32 v204, 1.0, v204
	v_add_f32_e32 v205, 1.0, v205
	v_add_f32_e32 v206, 1.0, v206
	v_add_f32_e32 v207, 1.0, v207
	v_rcp_f32_e32 v200, v200
	v_rcp_f32_e32 v201, v201
	v_rcp_f32_e32 v202, v202
	v_rcp_f32_e32 v203, v203
	v_rcp_f32_e32 v204, v204
	v_rcp_f32_e32 v205, v205
	v_rcp_f32_e32 v206, v206
	v_rcp_f32_e32 v207, v207
	v_pk_mul_f32 v[44:45], v[44:45], v[200:201]
	v_pk_mul_f32 v[46:47], v[46:47], v[202:203]
	v_pk_mul_f32 v[40:41], v[40:41], v[204:205]
	v_pk_mul_f32 v[42:43], v[42:43], v[206:207]
	v_pk_mul_f32 v[44:45], v[36:37], v[44:45]
	v_pk_mul_f32 v[46:47], v[38:39], v[46:47]
	v_pk_mul_f32 v[40:41], v[32:33], v[40:41]
	v_pk_mul_f32 v[42:43], v[34:35], v[42:43]
	v_cvt_pk_bf16_f32 v212, v44, v45
	v_cvt_pk_bf16_f32 v213, v46, v47
	v_cvt_pk_bf16_f32 v214, v40, v41
	v_cvt_pk_bf16_f32 v215, v42, v43
	s_mov_b64 s[100:101], 0xc6000
	v_lshl_add_u64 v[216:217], v[232:233], 0, s[100:101]
	global_store_dwordx4 v[216:217], v[212:215], off
	s_waitcnt lgkmcnt(1)
	v_pk_mul_f32 v[28:29], v[28:29], v[184:185] op_sel_hi:[1,0]
	v_pk_mul_f32 v[30:31], v[30:31], v[184:185] op_sel_hi:[1,0]
	v_pk_mul_f32 v[24:25], v[24:25], v[184:185] op_sel_hi:[1,0]
	v_pk_mul_f32 v[26:27], v[26:27], v[184:185] op_sel_hi:[1,0]
	v_pk_mul_f32 v[20:21], v[20:21], v[184:185] op_sel_hi:[1,0]
	v_pk_mul_f32 v[22:23], v[22:23], v[184:185] op_sel_hi:[1,0]
	v_pk_mul_f32 v[16:17], v[16:17], v[184:185] op_sel_hi:[1,0]
	v_pk_mul_f32 v[18:19], v[18:19], v[184:185] op_sel_hi:[1,0]
	v_pk_mul_f32 v[192:193], v[28:29], v[188:189] op_sel_hi:[1,0]
	v_pk_mul_f32 v[194:195], v[30:31], v[188:189] op_sel_hi:[1,0]
	v_pk_mul_f32 v[196:197], v[24:25], v[188:189] op_sel_hi:[1,0]
	v_pk_mul_f32 v[198:199], v[26:27], v[188:189] op_sel_hi:[1,0]
	v_exp_f32_e32 v192, v192
	v_exp_f32_e32 v193, v193
	v_exp_f32_e32 v194, v194
	v_exp_f32_e32 v195, v195
	v_exp_f32_e32 v196, v196
	v_exp_f32_e32 v197, v197
	v_exp_f32_e32 v198, v198
	v_exp_f32_e32 v199, v199
	v_add_f32_e32 v192, 1.0, v192
	v_add_f32_e32 v193, 1.0, v193
	v_add_f32_e32 v194, 1.0, v194
	v_add_f32_e32 v195, 1.0, v195
	v_add_f32_e32 v196, 1.0, v196
	v_add_f32_e32 v197, 1.0, v197
	v_add_f32_e32 v198, 1.0, v198
	v_add_f32_e32 v199, 1.0, v199
	v_rcp_f32_e32 v192, v192
	v_rcp_f32_e32 v193, v193
	v_rcp_f32_e32 v194, v194
	v_rcp_f32_e32 v195, v195
	v_rcp_f32_e32 v196, v196
	v_rcp_f32_e32 v197, v197
	v_rcp_f32_e32 v198, v198
	v_rcp_f32_e32 v199, v199
	v_pk_mul_f32 v[28:29], v[28:29], v[192:193]
	v_pk_mul_f32 v[30:31], v[30:31], v[194:195]
	v_pk_mul_f32 v[24:25], v[24:25], v[196:197]
	v_pk_mul_f32 v[26:27], v[26:27], v[198:199]
	v_pk_mul_f32 v[28:29], v[20:21], v[28:29]
	v_pk_mul_f32 v[30:31], v[22:23], v[30:31]
	v_pk_mul_f32 v[24:25], v[16:17], v[24:25]
	v_pk_mul_f32 v[26:27], v[18:19], v[26:27]
	v_cvt_pk_bf16_f32 v208, v28, v29
	v_cvt_pk_bf16_f32 v209, v30, v31
	v_cvt_pk_bf16_f32 v210, v24, v25
	v_cvt_pk_bf16_f32 v211, v26, v27
	s_mov_b64 s[100:101], 0xdc000
	v_lshl_add_u64 v[216:217], v[232:233], 0, s[100:101]
	global_store_dwordx4 v[216:217], v[208:211], off
	s_waitcnt lgkmcnt(0)
	v_pk_mul_f32 v[12:13], v[12:13], v[186:187] op_sel_hi:[1,0]
	v_pk_mul_f32 v[14:15], v[14:15], v[186:187] op_sel_hi:[1,0]
	v_pk_mul_f32 v[8:9], v[8:9], v[186:187] op_sel_hi:[1,0]
	v_pk_mul_f32 v[10:11], v[10:11], v[186:187] op_sel_hi:[1,0]
	v_pk_mul_f32 v[4:5], v[4:5], v[186:187] op_sel_hi:[1,0]
	v_pk_mul_f32 v[6:7], v[6:7], v[186:187] op_sel_hi:[1,0]
	v_pk_mul_f32 v[0:1], v[0:1], v[186:187] op_sel_hi:[1,0]
	v_pk_mul_f32 v[2:3], v[2:3], v[186:187] op_sel_hi:[1,0]
	v_pk_mul_f32 v[200:201], v[12:13], v[188:189] op_sel_hi:[1,0]
	v_pk_mul_f32 v[202:203], v[14:15], v[188:189] op_sel_hi:[1,0]
	v_pk_mul_f32 v[204:205], v[8:9], v[188:189] op_sel_hi:[1,0]
	v_pk_mul_f32 v[206:207], v[10:11], v[188:189] op_sel_hi:[1,0]
	v_exp_f32_e32 v200, v200
	v_exp_f32_e32 v201, v201
	v_exp_f32_e32 v202, v202
	v_exp_f32_e32 v203, v203
	v_exp_f32_e32 v204, v204
	v_exp_f32_e32 v205, v205
	v_exp_f32_e32 v206, v206
	v_exp_f32_e32 v207, v207
	v_add_f32_e32 v200, 1.0, v200
	v_add_f32_e32 v201, 1.0, v201
	v_add_f32_e32 v202, 1.0, v202
	v_add_f32_e32 v203, 1.0, v203
	v_add_f32_e32 v204, 1.0, v204
	v_add_f32_e32 v205, 1.0, v205
	v_add_f32_e32 v206, 1.0, v206
	v_add_f32_e32 v207, 1.0, v207
	v_rcp_f32_e32 v200, v200
	v_rcp_f32_e32 v201, v201
	v_rcp_f32_e32 v202, v202
	v_rcp_f32_e32 v203, v203
	v_rcp_f32_e32 v204, v204
	v_rcp_f32_e32 v205, v205
	v_rcp_f32_e32 v206, v206
	v_rcp_f32_e32 v207, v207
	v_pk_mul_f32 v[12:13], v[12:13], v[200:201]
	v_pk_mul_f32 v[14:15], v[14:15], v[202:203]
	v_pk_mul_f32 v[8:9], v[8:9], v[204:205]
	v_pk_mul_f32 v[10:11], v[10:11], v[206:207]
	v_pk_mul_f32 v[12:13], v[4:5], v[12:13]
	v_pk_mul_f32 v[14:15], v[6:7], v[14:15]
	v_pk_mul_f32 v[8:9], v[0:1], v[8:9]
	v_pk_mul_f32 v[10:11], v[2:3], v[10:11]
	v_cvt_pk_bf16_f32 v212, v12, v13
	v_cvt_pk_bf16_f32 v213, v14, v15
	v_cvt_pk_bf16_f32 v214, v8, v9
	v_cvt_pk_bf16_f32 v215, v10, v11
	s_mov_b64 s[100:101], 0xf2000
	v_lshl_add_u64 v[216:217], v[232:233], 0, s[100:101]
	global_store_dwordx4 v[216:217], v[212:215], off
	s_andn2_b64 vcc, exec, s[4:5]
	s_mov_b64 s[4:5], -1
	s_cbranch_vccnz .LBB0_1055
	s_andn2_b64 vcc, exec, s[0:1]
	s_cbranch_vccnz .LBB0_1054
	s_nop 0
	s_branch .LBB0_1054

.LBB0_1650:
	v_lshl_add_u32 v159, s12, 10, v152
	v_lshl_or_b32 v148, s13, 7, v153
	v_lshl_add_u32 v158, s30, 8, v150
	v_ashrrev_i32_e32 v149, 31, v148
	v_mov_b64_e32 v[146:147], s[16:17]
	v_mad_i64_i32 v[162:163], s[12:13], v158, s55, v[146:147]
	v_lshlrev_b64 v[148:149], 1, v[148:149]
	v_lshl_add_u64 v[162:163], v[162:163], 0, v[148:149]
	v_mov_b32_e32 v232, v162
	v_mov_b32_e32 v233, v163
	ds_read_b32 v172, v159
	ds_read_b32 v174, v159 offset:64
	ds_read_b32 v176, v159 offset:128
	ds_read_b32 v178, v159 offset:192
	ds_read_b32 v180, v159 offset:512
	ds_read_b32 v182, v159 offset:576
	ds_read_b32 v184, v159 offset:640
	ds_read_b32 v186, v159 offset:704
	v_mov_b32_e32 v188, 0xbfb8aa3b
	s_waitcnt lgkmcnt(7)
	v_pk_mul_f32 v[124:125], v[124:125], v[172:173] op_sel_hi:[1,0]
	v_pk_mul_f32 v[126:127], v[126:127], v[172:173] op_sel_hi:[1,0]
	v_pk_mul_f32 v[120:121], v[120:121], v[172:173] op_sel_hi:[1,0]
	v_pk_mul_f32 v[122:123], v[122:123], v[172:173] op_sel_hi:[1,0]
	v_pk_mul_f32 v[116:117], v[116:117], v[172:173] op_sel_hi:[1,0]
	v_pk_mul_f32 v[118:119], v[118:119], v[172:173] op_sel_hi:[1,0]
	v_pk_mul_f32 v[112:113], v[112:113], v[172:173] op_sel_hi:[1,0]
	v_pk_mul_f32 v[114:115], v[114:115], v[172:173] op_sel_hi:[1,0]
	v_pk_mul_f32 v[192:193], v[124:125], v[188:189] op_sel_hi:[1,0]
	v_pk_mul_f32 v[194:195], v[126:127], v[188:189] op_sel_hi:[1,0]
	v_pk_mul_f32 v[196:197], v[120:121], v[188:189] op_sel_hi:[1,0]
	v_pk_mul_f32 v[198:199], v[122:123], v[188:189] op_sel_hi:[1,0]
	v_exp_f32_e32 v192, v192
	v_exp_f32_e32 v193, v193
	v_exp_f32_e32 v194, v194
	v_exp_f32_e32 v195, v195
	v_exp_f32_e32 v196, v196
	v_exp_f32_e32 v197, v197
	v_exp_f32_e32 v198, v198
	v_exp_f32_e32 v199, v199
	v_add_f32_e32 v192, 1.0, v192
	v_add_f32_e32 v193, 1.0, v193
	v_add_f32_e32 v194, 1.0, v194
	v_add_f32_e32 v195, 1.0, v195
	v_add_f32_e32 v196, 1.0, v196
	v_add_f32_e32 v197, 1.0, v197
	v_add_f32_e32 v198, 1.0, v198
	v_add_f32_e32 v199, 1.0, v199
	v_rcp_f32_e32 v192, v192
	v_rcp_f32_e32 v193, v193
	v_rcp_f32_e32 v194, v194
	v_rcp_f32_e32 v195, v195
	v_rcp_f32_e32 v196, v196
	v_rcp_f32_e32 v197, v197
	v_rcp_f32_e32 v198, v198
	v_rcp_f32_e32 v199, v199
	v_pk_mul_f32 v[124:125], v[124:125], v[192:193]
	v_pk_mul_f32 v[126:127], v[126:127], v[194:195]
	v_pk_mul_f32 v[120:121], v[120:121], v[196:197]
	v_pk_mul_f32 v[122:123], v[122:123], v[198:199]
	v_pk_mul_f32 v[124:125], v[116:117], v[124:125]
	v_pk_mul_f32 v[126:127], v[118:119], v[126:127]
	v_pk_mul_f32 v[120:121], v[112:113], v[120:121]
	v_pk_mul_f32 v[122:123], v[114:115], v[122:123]
	v_cvt_pk_bf16_f32 v208, v124, v125
	v_cvt_pk_bf16_f32 v209, v126, v127
	v_cvt_pk_bf16_f32 v210, v120, v121
	v_cvt_pk_bf16_f32 v211, v122, v123
	global_store_dwordx4 v[232:233], v[208:211], off
	s_waitcnt lgkmcnt(6)
	v_pk_mul_f32 v[108:109], v[108:109], v[174:175] op_sel_hi:[1,0]
	v_pk_mul_f32 v[110:111], v[110:111], v[174:175] op_sel_hi:[1,0]
	v_pk_mul_f32 v[104:105], v[104:105], v[174:175] op_sel_hi:[1,0]
	v_pk_mul_f32 v[106:107], v[106:107], v[174:175] op_sel_hi:[1,0]
	v_pk_mul_f32 v[100:101], v[100:101], v[174:175] op_sel_hi:[1,0]
	v_pk_mul_f32 v[102:103], v[102:103], v[174:175] op_sel_hi:[1,0]
	v_pk_mul_f32 v[96:97], v[96:97], v[174:175] op_sel_hi:[1,0]
	v_pk_mul_f32 v[98:99], v[98:99], v[174:175] op_sel_hi:[1,0]
	v_pk_mul_f32 v[200:201], v[108:109], v[188:189] op_sel_hi:[1,0]
	v_pk_mul_f32 v[202:203], v[110:111], v[188:189] op_sel_hi:[1,0]
	v_pk_mul_f32 v[204:205], v[104:105], v[188:189] op_sel_hi:[1,0]
	v_pk_mul_f32 v[206:207], v[106:107], v[188:189] op_sel_hi:[1,0]
	v_exp_f32_e32 v200, v200
	v_exp_f32_e32 v201, v201
	v_exp_f32_e32 v202, v202
	v_exp_f32_e32 v203, v203
	v_exp_f32_e32 v204, v204
	v_exp_f32_e32 v205, v205
	v_exp_f32_e32 v206, v206
	v_exp_f32_e32 v207, v207
	v_add_f32_e32 v200, 1.0, v200
	v_add_f32_e32 v201, 1.0, v201
	v_add_f32_e32 v202, 1.0, v202
	v_add_f32_e32 v203, 1.0, v203
	v_add_f32_e32 v204, 1.0, v204
	v_add_f32_e32 v205, 1.0, v205
	v_add_f32_e32 v206, 1.0, v206
	v_add_f32_e32 v207, 1.0, v207
	v_rcp_f32_e32 v200, v200
	v_rcp_f32_e32 v201, v201
	v_rcp_f32_e32 v202, v202
	v_rcp_f32_e32 v203, v203
	v_rcp_f32_e32 v204, v204
	v_rcp_f32_e32 v205, v205
	v_rcp_f32_e32 v206, v206
	v_rcp_f32_e32 v207, v207
	v_pk_mul_f32 v[108:109], v[108:109], v[200:201]
	v_pk_mul_f32 v[110:111], v[110:111], v[202:203]
	v_pk_mul_f32 v[104:105], v[104:105], v[204:205]
	v_pk_mul_f32 v[106:107], v[106:107], v[206:207]
	v_pk_mul_f32 v[108:109], v[100:101], v[108:109]
	v_pk_mul_f32 v[110:111], v[102:103], v[110:111]
	v_pk_mul_f32 v[104:105], v[96:97], v[104:105]
	v_pk_mul_f32 v[106:107], v[98:99], v[106:107]
	v_cvt_pk_bf16_f32 v212, v108, v109
	v_cvt_pk_bf16_f32 v213, v110, v111
	v_cvt_pk_bf16_f32 v214, v104, v105
	v_cvt_pk_bf16_f32 v215, v106, v107
	s_mov_b64 s[100:101], 0x16000
	v_lshl_add_u64 v[216:217], v[232:233], 0, s[100:101]
	global_store_dwordx4 v[216:217], v[212:215], off
	s_waitcnt lgkmcnt(5)
	v_pk_mul_f32 v[92:93], v[92:93], v[176:177] op_sel_hi:[1,0]
	v_pk_mul_f32 v[94:95], v[94:95], v[176:177] op_sel_hi:[1,0]
	v_pk_mul_f32 v[88:89], v[88:89], v[176:177] op_sel_hi:[1,0]
	v_pk_mul_f32 v[90:91], v[90:91], v[176:177] op_sel_hi:[1,0]
	v_pk_mul_f32 v[84:85], v[84:85], v[176:177] op_sel_hi:[1,0]
	v_pk_mul_f32 v[86:87], v[86:87], v[176:177] op_sel_hi:[1,0]
	v_pk_mul_f32 v[80:81], v[80:81], v[176:177] op_sel_hi:[1,0]
	v_pk_mul_f32 v[82:83], v[82:83], v[176:177] op_sel_hi:[1,0]
	v_pk_mul_f32 v[192:193], v[92:93], v[188:189] op_sel_hi:[1,0]
	v_pk_mul_f32 v[194:195], v[94:95], v[188:189] op_sel_hi:[1,0]
	v_pk_mul_f32 v[196:197], v[88:89], v[188:189] op_sel_hi:[1,0]
	v_pk_mul_f32 v[198:199], v[90:91], v[188:189] op_sel_hi:[1,0]
	v_exp_f32_e32 v192, v192
	v_exp_f32_e32 v193, v193
	v_exp_f32_e32 v194, v194
	v_exp_f32_e32 v195, v195
	v_exp_f32_e32 v196, v196
	v_exp_f32_e32 v197, v197
	v_exp_f32_e32 v198, v198
	v_exp_f32_e32 v199, v199
	v_add_f32_e32 v192, 1.0, v192
	v_add_f32_e32 v193, 1.0, v193
	v_add_f32_e32 v194, 1.0, v194
	v_add_f32_e32 v195, 1.0, v195
	v_add_f32_e32 v196, 1.0, v196
	v_add_f32_e32 v197, 1.0, v197
	v_add_f32_e32 v198, 1.0, v198
	v_add_f32_e32 v199, 1.0, v199
	v_rcp_f32_e32 v192, v192
	v_rcp_f32_e32 v193, v193
	v_rcp_f32_e32 v194, v194
	v_rcp_f32_e32 v195, v195
	v_rcp_f32_e32 v196, v196
	v_rcp_f32_e32 v197, v197
	v_rcp_f32_e32 v198, v198
	v_rcp_f32_e32 v199, v199
	v_pk_mul_f32 v[92:93], v[92:93], v[192:193]
	v_pk_mul_f32 v[94:95], v[94:95], v[194:195]
	v_pk_mul_f32 v[88:89], v[88:89], v[196:197]
	v_pk_mul_f32 v[90:91], v[90:91], v[198:199]
	v_pk_mul_f32 v[92:93], v[84:85], v[92:93]
	v_pk_mul_f32 v[94:95], v[86:87], v[94:95]
	v_pk_mul_f32 v[88:89], v[80:81], v[88:89]
	v_pk_mul_f32 v[90:91], v[82:83], v[90:91]
	v_cvt_pk_bf16_f32 v208, v92, v93
	v_cvt_pk_bf16_f32 v209, v94, v95
	v_cvt_pk_bf16_f32 v210, v88, v89
	v_cvt_pk_bf16_f32 v211, v90, v91
	s_mov_b64 s[100:101], 0x2c000
	v_lshl_add_u64 v[216:217], v[232:233], 0, s[100:101]
	global_store_dwordx4 v[216:217], v[208:211], off
	s_waitcnt lgkmcnt(4)
	v_pk_mul_f32 v[76:77], v[76:77], v[178:179] op_sel_hi:[1,0]
	v_pk_mul_f32 v[78:79], v[78:79], v[178:179] op_sel_hi:[1,0]
	v_pk_mul_f32 v[72:73], v[72:73], v[178:179] op_sel_hi:[1,0]
	v_pk_mul_f32 v[74:75], v[74:75], v[178:179] op_sel_hi:[1,0]
	v_pk_mul_f32 v[68:69], v[68:69], v[178:179] op_sel_hi:[1,0]
	v_pk_mul_f32 v[70:71], v[70:71], v[178:179] op_sel_hi:[1,0]
	v_pk_mul_f32 v[64:65], v[64:65], v[178:179] op_sel_hi:[1,0]
	v_pk_mul_f32 v[66:67], v[66:67], v[178:179] op_sel_hi:[1,0]
	v_pk_mul_f32 v[200:201], v[76:77], v[188:189] op_sel_hi:[1,0]
	v_pk_mul_f32 v[202:203], v[78:79], v[188:189] op_sel_hi:[1,0]
	v_pk_mul_f32 v[204:205], v[72:73], v[188:189] op_sel_hi:[1,0]
	v_pk_mul_f32 v[206:207], v[74:75], v[188:189] op_sel_hi:[1,0]
	v_exp_f32_e32 v200, v200
	v_exp_f32_e32 v201, v201
	v_exp_f32_e32 v202, v202
	v_exp_f32_e32 v203, v203
	v_exp_f32_e32 v204, v204
	v_exp_f32_e32 v205, v205
	v_exp_f32_e32 v206, v206
	v_exp_f32_e32 v207, v207
	v_add_f32_e32 v200, 1.0, v200
	v_add_f32_e32 v201, 1.0, v201
	v_add_f32_e32 v202, 1.0, v202
	v_add_f32_e32 v203, 1.0, v203
	v_add_f32_e32 v204, 1.0, v204
	v_add_f32_e32 v205, 1.0, v205
	v_add_f32_e32 v206, 1.0, v206
	v_add_f32_e32 v207, 1.0, v207
	v_rcp_f32_e32 v200, v200
	v_rcp_f32_e32 v201, v201
	v_rcp_f32_e32 v202, v202
	v_rcp_f32_e32 v203, v203
	v_rcp_f32_e32 v204, v204
	v_rcp_f32_e32 v205, v205
	v_rcp_f32_e32 v206, v206
	v_rcp_f32_e32 v207, v207
	v_pk_mul_f32 v[76:77], v[76:77], v[200:201]
	v_pk_mul_f32 v[78:79], v[78:79], v[202:203]
	v_pk_mul_f32 v[72:73], v[72:73], v[204:205]
	v_pk_mul_f32 v[74:75], v[74:75], v[206:207]
	v_pk_mul_f32 v[76:77], v[68:69], v[76:77]
	v_pk_mul_f32 v[78:79], v[70:71], v[78:79]
	v_pk_mul_f32 v[72:73], v[64:65], v[72:73]
	v_pk_mul_f32 v[74:75], v[66:67], v[74:75]
	v_cvt_pk_bf16_f32 v212, v76, v77
	v_cvt_pk_bf16_f32 v213, v78, v79
	v_cvt_pk_bf16_f32 v214, v72, v73
	v_cvt_pk_bf16_f32 v215, v74, v75
	s_mov_b64 s[100:101], 0x42000
	v_lshl_add_u64 v[216:217], v[232:233], 0, s[100:101]
	global_store_dwordx4 v[216:217], v[212:215], off
	s_waitcnt lgkmcnt(3)
	v_pk_mul_f32 v[60:61], v[60:61], v[180:181] op_sel_hi:[1,0]
	v_pk_mul_f32 v[62:63], v[62:63], v[180:181] op_sel_hi:[1,0]
	v_pk_mul_f32 v[56:57], v[56:57], v[180:181] op_sel_hi:[1,0]
	v_pk_mul_f32 v[58:59], v[58:59], v[180:181] op_sel_hi:[1,0]
	v_pk_mul_f32 v[52:53], v[52:53], v[180:181] op_sel_hi:[1,0]
	v_pk_mul_f32 v[54:55], v[54:55], v[180:181] op_sel_hi:[1,0]
	v_pk_mul_f32 v[48:49], v[48:49], v[180:181] op_sel_hi:[1,0]
	v_pk_mul_f32 v[50:51], v[50:51], v[180:181] op_sel_hi:[1,0]
	v_pk_mul_f32 v[192:193], v[60:61], v[188:189] op_sel_hi:[1,0]
	v_pk_mul_f32 v[194:195], v[62:63], v[188:189] op_sel_hi:[1,0]
	v_pk_mul_f32 v[196:197], v[56:57], v[188:189] op_sel_hi:[1,0]
	v_pk_mul_f32 v[198:199], v[58:59], v[188:189] op_sel_hi:[1,0]
	v_exp_f32_e32 v192, v192
	v_exp_f32_e32 v193, v193
	v_exp_f32_e32 v194, v194
	v_exp_f32_e32 v195, v195
	v_exp_f32_e32 v196, v196
	v_exp_f32_e32 v197, v197
	v_exp_f32_e32 v198, v198
	v_exp_f32_e32 v199, v199
	v_add_f32_e32 v192, 1.0, v192
	v_add_f32_e32 v193, 1.0, v193
	v_add_f32_e32 v194, 1.0, v194
	v_add_f32_e32 v195, 1.0, v195
	v_add_f32_e32 v196, 1.0, v196
	v_add_f32_e32 v197, 1.0, v197
	v_add_f32_e32 v198, 1.0, v198
	v_add_f32_e32 v199, 1.0, v199
	v_rcp_f32_e32 v192, v192
	v_rcp_f32_e32 v193, v193
	v_rcp_f32_e32 v194, v194
	v_rcp_f32_e32 v195, v195
	v_rcp_f32_e32 v196, v196
	v_rcp_f32_e32 v197, v197
	v_rcp_f32_e32 v198, v198
	v_rcp_f32_e32 v199, v199
	v_pk_mul_f32 v[60:61], v[60:61], v[192:193]
	v_pk_mul_f32 v[62:63], v[62:63], v[194:195]
	v_pk_mul_f32 v[56:57], v[56:57], v[196:197]
	v_pk_mul_f32 v[58:59], v[58:59], v[198:199]
	v_pk_mul_f32 v[60:61], v[52:53], v[60:61]
	v_pk_mul_f32 v[62:63], v[54:55], v[62:63]
	v_pk_mul_f32 v[56:57], v[48:49], v[56:57]
	v_pk_mul_f32 v[58:59], v[50:51], v[58:59]
	v_cvt_pk_bf16_f32 v208, v60, v61
	v_cvt_pk_bf16_f32 v209, v62, v63
	v_cvt_pk_bf16_f32 v210, v56, v57
	v_cvt_pk_bf16_f32 v211, v58, v59
	s_mov_b64 s[100:101], 0xb0000
	v_lshl_add_u64 v[216:217], v[232:233], 0, s[100:101]
	global_store_dwordx4 v[216:217], v[208:211], off
	s_waitcnt lgkmcnt(2)
	v_pk_mul_f32 v[44:45], v[44:45], v[182:183] op_sel_hi:[1,0]
	v_pk_mul_f32 v[46:47], v[46:47], v[182:183] op_sel_hi:[1,0]
	v_pk_mul_f32 v[40:41], v[40:41], v[182:183] op_sel_hi:[1,0]
	v_pk_mul_f32 v[42:43], v[42:43], v[182:183] op_sel_hi:[1,0]
	v_pk_mul_f32 v[36:37], v[36:37], v[182:183] op_sel_hi:[1,0]
	v_pk_mul_f32 v[38:39], v[38:39], v[182:183] op_sel_hi:[1,0]
	v_pk_mul_f32 v[32:33], v[32:33], v[182:183] op_sel_hi:[1,0]
	v_pk_mul_f32 v[34:35], v[34:35], v[182:183] op_sel_hi:[1,0]
	v_pk_mul_f32 v[200:201], v[44:45], v[188:189] op_sel_hi:[1,0]
	v_pk_mul_f32 v[202:203], v[46:47], v[188:189] op_sel_hi:[1,0]
	v_pk_mul_f32 v[204:205], v[40:41], v[188:189] op_sel_hi:[1,0]
	v_pk_mul_f32 v[206:207], v[42:43], v[188:189] op_sel_hi:[1,0]
	v_exp_f32_e32 v200, v200
	v_exp_f32_e32 v201, v201
	v_exp_f32_e32 v202, v202
	v_exp_f32_e32 v203, v203
	v_exp_f32_e32 v204, v204
	v_exp_f32_e32 v205, v205
	v_exp_f32_e32 v206, v206
	v_exp_f32_e32 v207, v207
	v_add_f32_e32 v200, 1.0, v200
	v_add_f32_e32 v201, 1.0, v201
	v_add_f32_e32 v202, 1.0, v202
	v_add_f32_e32 v203, 1.0, v203
	v_add_f32_e32 v204, 1.0, v204
	v_add_f32_e32 v205, 1.0, v205
	v_add_f32_e32 v206, 1.0, v206
	v_add_f32_e32 v207, 1.0, v207
	v_rcp_f32_e32 v200, v200
	v_rcp_f32_e32 v201, v201
	v_rcp_f32_e32 v202, v202
	v_rcp_f32_e32 v203, v203
	v_rcp_f32_e32 v204, v204
	v_rcp_f32_e32 v205, v205
	v_rcp_f32_e32 v206, v206
	v_rcp_f32_e32 v207, v207
	v_pk_mul_f32 v[44:45], v[44:45], v[200:201]
	v_pk_mul_f32 v[46:47], v[46:47], v[202:203]
	v_pk_mul_f32 v[40:41], v[40:41], v[204:205]
	v_pk_mul_f32 v[42:43], v[42:43], v[206:207]
	v_pk_mul_f32 v[44:45], v[36:37], v[44:45]
	v_pk_mul_f32 v[46:47], v[38:39], v[46:47]
	v_pk_mul_f32 v[40:41], v[32:33], v[40:41]
	v_pk_mul_f32 v[42:43], v[34:35], v[42:43]
	v_cvt_pk_bf16_f32 v212, v44, v45
	v_cvt_pk_bf16_f32 v213, v46, v47
	v_cvt_pk_bf16_f32 v214, v40, v41
	v_cvt_pk_bf16_f32 v215, v42, v43
	s_mov_b64 s[100:101], 0xc6000
	v_lshl_add_u64 v[216:217], v[232:233], 0, s[100:101]
	global_store_dwordx4 v[216:217], v[212:215], off
	s_waitcnt lgkmcnt(1)
	v_pk_mul_f32 v[28:29], v[28:29], v[184:185] op_sel_hi:[1,0]
	v_pk_mul_f32 v[30:31], v[30:31], v[184:185] op_sel_hi:[1,0]
	v_pk_mul_f32 v[24:25], v[24:25], v[184:185] op_sel_hi:[1,0]
	v_pk_mul_f32 v[26:27], v[26:27], v[184:185] op_sel_hi:[1,0]
	v_pk_mul_f32 v[20:21], v[20:21], v[184:185] op_sel_hi:[1,0]
	v_pk_mul_f32 v[22:23], v[22:23], v[184:185] op_sel_hi:[1,0]
	v_pk_mul_f32 v[16:17], v[16:17], v[184:185] op_sel_hi:[1,0]
	v_pk_mul_f32 v[18:19], v[18:19], v[184:185] op_sel_hi:[1,0]
	v_pk_mul_f32 v[192:193], v[28:29], v[188:189] op_sel_hi:[1,0]
	v_pk_mul_f32 v[194:195], v[30:31], v[188:189] op_sel_hi:[1,0]
	v_pk_mul_f32 v[196:197], v[24:25], v[188:189] op_sel_hi:[1,0]
	v_pk_mul_f32 v[198:199], v[26:27], v[188:189] op_sel_hi:[1,0]
	v_exp_f32_e32 v192, v192
	v_exp_f32_e32 v193, v193
	v_exp_f32_e32 v194, v194
	v_exp_f32_e32 v195, v195
	v_exp_f32_e32 v196, v196
	v_exp_f32_e32 v197, v197
	v_exp_f32_e32 v198, v198
	v_exp_f32_e32 v199, v199
	v_add_f32_e32 v192, 1.0, v192
	v_add_f32_e32 v193, 1.0, v193
	v_add_f32_e32 v194, 1.0, v194
	v_add_f32_e32 v195, 1.0, v195
	v_add_f32_e32 v196, 1.0, v196
	v_add_f32_e32 v197, 1.0, v197
	v_add_f32_e32 v198, 1.0, v198
	v_add_f32_e32 v199, 1.0, v199
	v_rcp_f32_e32 v192, v192
	v_rcp_f32_e32 v193, v193
	v_rcp_f32_e32 v194, v194
	v_rcp_f32_e32 v195, v195
	v_rcp_f32_e32 v196, v196
	v_rcp_f32_e32 v197, v197
	v_rcp_f32_e32 v198, v198
	v_rcp_f32_e32 v199, v199
	v_pk_mul_f32 v[28:29], v[28:29], v[192:193]
	v_pk_mul_f32 v[30:31], v[30:31], v[194:195]
	v_pk_mul_f32 v[24:25], v[24:25], v[196:197]
	v_pk_mul_f32 v[26:27], v[26:27], v[198:199]
	v_pk_mul_f32 v[28:29], v[20:21], v[28:29]
	v_pk_mul_f32 v[30:31], v[22:23], v[30:31]
	v_pk_mul_f32 v[24:25], v[16:17], v[24:25]
	v_pk_mul_f32 v[26:27], v[18:19], v[26:27]
	v_cvt_pk_bf16_f32 v208, v28, v29
	v_cvt_pk_bf16_f32 v209, v30, v31
	v_cvt_pk_bf16_f32 v210, v24, v25
	v_cvt_pk_bf16_f32 v211, v26, v27
	s_mov_b64 s[100:101], 0xdc000
	v_lshl_add_u64 v[216:217], v[232:233], 0, s[100:101]
	global_store_dwordx4 v[216:217], v[208:211], off
	s_waitcnt lgkmcnt(0)
	v_pk_mul_f32 v[12:13], v[12:13], v[186:187] op_sel_hi:[1,0]
	v_pk_mul_f32 v[14:15], v[14:15], v[186:187] op_sel_hi:[1,0]
	v_pk_mul_f32 v[8:9], v[8:9], v[186:187] op_sel_hi:[1,0]
	v_pk_mul_f32 v[10:11], v[10:11], v[186:187] op_sel_hi:[1,0]
	v_pk_mul_f32 v[4:5], v[4:5], v[186:187] op_sel_hi:[1,0]
	v_pk_mul_f32 v[6:7], v[6:7], v[186:187] op_sel_hi:[1,0]
	v_pk_mul_f32 v[0:1], v[0:1], v[186:187] op_sel_hi:[1,0]
	v_pk_mul_f32 v[2:3], v[2:3], v[186:187] op_sel_hi:[1,0]
	v_pk_mul_f32 v[200:201], v[12:13], v[188:189] op_sel_hi:[1,0]
	v_pk_mul_f32 v[202:203], v[14:15], v[188:189] op_sel_hi:[1,0]
	v_pk_mul_f32 v[204:205], v[8:9], v[188:189] op_sel_hi:[1,0]
	v_pk_mul_f32 v[206:207], v[10:11], v[188:189] op_sel_hi:[1,0]
	v_exp_f32_e32 v200, v200
	v_exp_f32_e32 v201, v201
	v_exp_f32_e32 v202, v202
	v_exp_f32_e32 v203, v203
	v_exp_f32_e32 v204, v204
	v_exp_f32_e32 v205, v205
	v_exp_f32_e32 v206, v206
	v_exp_f32_e32 v207, v207
	v_add_f32_e32 v200, 1.0, v200
	v_add_f32_e32 v201, 1.0, v201
	v_add_f32_e32 v202, 1.0, v202
	v_add_f32_e32 v203, 1.0, v203
	v_add_f32_e32 v204, 1.0, v204
	v_add_f32_e32 v205, 1.0, v205
	v_add_f32_e32 v206, 1.0, v206
	v_add_f32_e32 v207, 1.0, v207
	v_rcp_f32_e32 v200, v200
	v_rcp_f32_e32 v201, v201
	v_rcp_f32_e32 v202, v202
	v_rcp_f32_e32 v203, v203
	v_rcp_f32_e32 v204, v204
	v_rcp_f32_e32 v205, v205
	v_rcp_f32_e32 v206, v206
	v_rcp_f32_e32 v207, v207
	v_pk_mul_f32 v[12:13], v[12:13], v[200:201]
	v_pk_mul_f32 v[14:15], v[14:15], v[202:203]
	v_pk_mul_f32 v[8:9], v[8:9], v[204:205]
	v_pk_mul_f32 v[10:11], v[10:11], v[206:207]
	v_pk_mul_f32 v[12:13], v[4:5], v[12:13]
	v_pk_mul_f32 v[14:15], v[6:7], v[14:15]
	v_pk_mul_f32 v[8:9], v[0:1], v[8:9]
	v_pk_mul_f32 v[10:11], v[2:3], v[10:11]
	v_cvt_pk_bf16_f32 v212, v12, v13
	v_cvt_pk_bf16_f32 v213, v14, v15
	v_cvt_pk_bf16_f32 v214, v8, v9
	v_cvt_pk_bf16_f32 v215, v10, v11
	s_mov_b64 s[100:101], 0xf2000
	v_lshl_add_u64 v[216:217], v[232:233], 0, s[100:101]
	global_store_dwordx4 v[216:217], v[212:215], off
	s_andn2_b64 vcc, exec, s[4:5]
	s_mov_b64 s[4:5], -1
	s_cbranch_vccnz .LBB0_1643
	s_andn2_b64 vcc, exec, s[0:1]
	s_cbranch_vccnz .LBB0_1642
	s_nop 0
	s_branch .LBB0_1642

.LBB0_2094:
	v_lshl_add_u32 v157, s12, 10, v151
	v_lshl_or_b32 v148, s13, 7, v152
	v_lshl_add_u32 v156, s24, 8, v129
	v_ashrrev_i32_e32 v149, 31, v148
	v_mov_b64_e32 v[146:147], s[16:17]
	v_mad_i64_i32 v[160:161], s[12:13], v156, s49, v[146:147]
	v_lshlrev_b64 v[148:149], 1, v[148:149]
	v_lshl_add_u64 v[160:161], v[160:161], 0, v[148:149]
	v_mov_b32_e32 v232, v160
	v_mov_b32_e32 v233, v161
	ds_read_b32 v172, v157
	ds_read_b32 v174, v157 offset:64
	ds_read_b32 v176, v157 offset:128
	ds_read_b32 v178, v157 offset:192
	ds_read_b32 v180, v157 offset:512
	ds_read_b32 v182, v157 offset:576
	ds_read_b32 v184, v157 offset:640
	ds_read_b32 v186, v157 offset:704
	v_mov_b32_e32 v188, 0xbfb8aa3b
	s_waitcnt lgkmcnt(7)
	v_pk_mul_f32 v[124:125], v[124:125], v[172:173] op_sel_hi:[1,0]
	v_pk_mul_f32 v[126:127], v[126:127], v[172:173] op_sel_hi:[1,0]
	v_pk_mul_f32 v[120:121], v[120:121], v[172:173] op_sel_hi:[1,0]
	v_pk_mul_f32 v[122:123], v[122:123], v[172:173] op_sel_hi:[1,0]
	v_pk_mul_f32 v[116:117], v[116:117], v[172:173] op_sel_hi:[1,0]
	v_pk_mul_f32 v[118:119], v[118:119], v[172:173] op_sel_hi:[1,0]
	v_pk_mul_f32 v[112:113], v[112:113], v[172:173] op_sel_hi:[1,0]
	v_pk_mul_f32 v[114:115], v[114:115], v[172:173] op_sel_hi:[1,0]
	v_pk_mul_f32 v[192:193], v[124:125], v[188:189] op_sel_hi:[1,0]
	v_pk_mul_f32 v[194:195], v[126:127], v[188:189] op_sel_hi:[1,0]
	v_pk_mul_f32 v[196:197], v[120:121], v[188:189] op_sel_hi:[1,0]
	v_pk_mul_f32 v[198:199], v[122:123], v[188:189] op_sel_hi:[1,0]
	v_exp_f32_e32 v192, v192
	v_exp_f32_e32 v193, v193
	v_exp_f32_e32 v194, v194
	v_exp_f32_e32 v195, v195
	v_exp_f32_e32 v196, v196
	v_exp_f32_e32 v197, v197
	v_exp_f32_e32 v198, v198
	v_exp_f32_e32 v199, v199
	v_add_f32_e32 v192, 1.0, v192
	v_add_f32_e32 v193, 1.0, v193
	v_add_f32_e32 v194, 1.0, v194
	v_add_f32_e32 v195, 1.0, v195
	v_add_f32_e32 v196, 1.0, v196
	v_add_f32_e32 v197, 1.0, v197
	v_add_f32_e32 v198, 1.0, v198
	v_add_f32_e32 v199, 1.0, v199
	v_rcp_f32_e32 v192, v192
	v_rcp_f32_e32 v193, v193
	v_rcp_f32_e32 v194, v194
	v_rcp_f32_e32 v195, v195
	v_rcp_f32_e32 v196, v196
	v_rcp_f32_e32 v197, v197
	v_rcp_f32_e32 v198, v198
	v_rcp_f32_e32 v199, v199
	v_pk_mul_f32 v[124:125], v[124:125], v[192:193]
	v_pk_mul_f32 v[126:127], v[126:127], v[194:195]
	v_pk_mul_f32 v[120:121], v[120:121], v[196:197]
	v_pk_mul_f32 v[122:123], v[122:123], v[198:199]
	v_pk_mul_f32 v[124:125], v[116:117], v[124:125]
	v_pk_mul_f32 v[126:127], v[118:119], v[126:127]
	v_pk_mul_f32 v[120:121], v[112:113], v[120:121]
	v_pk_mul_f32 v[122:123], v[114:115], v[122:123]
	v_cvt_pk_bf16_f32 v208, v124, v125
	v_cvt_pk_bf16_f32 v209, v126, v127
	v_cvt_pk_bf16_f32 v210, v120, v121
	v_cvt_pk_bf16_f32 v211, v122, v123
	global_store_dwordx4 v[232:233], v[208:211], off
	s_waitcnt lgkmcnt(6)
	v_pk_mul_f32 v[108:109], v[108:109], v[174:175] op_sel_hi:[1,0]
	v_pk_mul_f32 v[110:111], v[110:111], v[174:175] op_sel_hi:[1,0]
	v_pk_mul_f32 v[104:105], v[104:105], v[174:175] op_sel_hi:[1,0]
	v_pk_mul_f32 v[106:107], v[106:107], v[174:175] op_sel_hi:[1,0]
	v_pk_mul_f32 v[100:101], v[100:101], v[174:175] op_sel_hi:[1,0]
	v_pk_mul_f32 v[102:103], v[102:103], v[174:175] op_sel_hi:[1,0]
	v_pk_mul_f32 v[96:97], v[96:97], v[174:175] op_sel_hi:[1,0]
	v_pk_mul_f32 v[98:99], v[98:99], v[174:175] op_sel_hi:[1,0]
	v_pk_mul_f32 v[200:201], v[108:109], v[188:189] op_sel_hi:[1,0]
	v_pk_mul_f32 v[202:203], v[110:111], v[188:189] op_sel_hi:[1,0]
	v_pk_mul_f32 v[204:205], v[104:105], v[188:189] op_sel_hi:[1,0]
	v_pk_mul_f32 v[206:207], v[106:107], v[188:189] op_sel_hi:[1,0]
	v_exp_f32_e32 v200, v200
	v_exp_f32_e32 v201, v201
	v_exp_f32_e32 v202, v202
	v_exp_f32_e32 v203, v203
	v_exp_f32_e32 v204, v204
	v_exp_f32_e32 v205, v205
	v_exp_f32_e32 v206, v206
	v_exp_f32_e32 v207, v207
	v_add_f32_e32 v200, 1.0, v200
	v_add_f32_e32 v201, 1.0, v201
	v_add_f32_e32 v202, 1.0, v202
	v_add_f32_e32 v203, 1.0, v203
	v_add_f32_e32 v204, 1.0, v204
	v_add_f32_e32 v205, 1.0, v205
	v_add_f32_e32 v206, 1.0, v206
	v_add_f32_e32 v207, 1.0, v207
	v_rcp_f32_e32 v200, v200
	v_rcp_f32_e32 v201, v201
	v_rcp_f32_e32 v202, v202
	v_rcp_f32_e32 v203, v203
	v_rcp_f32_e32 v204, v204
	v_rcp_f32_e32 v205, v205
	v_rcp_f32_e32 v206, v206
	v_rcp_f32_e32 v207, v207
	v_pk_mul_f32 v[108:109], v[108:109], v[200:201]
	v_pk_mul_f32 v[110:111], v[110:111], v[202:203]
	v_pk_mul_f32 v[104:105], v[104:105], v[204:205]
	v_pk_mul_f32 v[106:107], v[106:107], v[206:207]
	v_pk_mul_f32 v[108:109], v[100:101], v[108:109]
	v_pk_mul_f32 v[110:111], v[102:103], v[110:111]
	v_pk_mul_f32 v[104:105], v[96:97], v[104:105]
	v_pk_mul_f32 v[106:107], v[98:99], v[106:107]
	v_cvt_pk_bf16_f32 v212, v108, v109
	v_cvt_pk_bf16_f32 v213, v110, v111
	v_cvt_pk_bf16_f32 v214, v104, v105
	v_cvt_pk_bf16_f32 v215, v106, v107
	s_mov_b64 s[100:101], 0x16000
	v_lshl_add_u64 v[216:217], v[232:233], 0, s[100:101]
	global_store_dwordx4 v[216:217], v[212:215], off
	s_waitcnt lgkmcnt(5)
	v_pk_mul_f32 v[92:93], v[92:93], v[176:177] op_sel_hi:[1,0]
	v_pk_mul_f32 v[94:95], v[94:95], v[176:177] op_sel_hi:[1,0]
	v_pk_mul_f32 v[88:89], v[88:89], v[176:177] op_sel_hi:[1,0]
	v_pk_mul_f32 v[90:91], v[90:91], v[176:177] op_sel_hi:[1,0]
	v_pk_mul_f32 v[84:85], v[84:85], v[176:177] op_sel_hi:[1,0]
	v_pk_mul_f32 v[86:87], v[86:87], v[176:177] op_sel_hi:[1,0]
	v_pk_mul_f32 v[80:81], v[80:81], v[176:177] op_sel_hi:[1,0]
	v_pk_mul_f32 v[82:83], v[82:83], v[176:177] op_sel_hi:[1,0]
	v_pk_mul_f32 v[192:193], v[92:93], v[188:189] op_sel_hi:[1,0]
	v_pk_mul_f32 v[194:195], v[94:95], v[188:189] op_sel_hi:[1,0]
	v_pk_mul_f32 v[196:197], v[88:89], v[188:189] op_sel_hi:[1,0]
	v_pk_mul_f32 v[198:199], v[90:91], v[188:189] op_sel_hi:[1,0]
	v_exp_f32_e32 v192, v192
	v_exp_f32_e32 v193, v193
	v_exp_f32_e32 v194, v194
	v_exp_f32_e32 v195, v195
	v_exp_f32_e32 v196, v196
	v_exp_f32_e32 v197, v197
	v_exp_f32_e32 v198, v198
	v_exp_f32_e32 v199, v199
	v_add_f32_e32 v192, 1.0, v192
	v_add_f32_e32 v193, 1.0, v193
	v_add_f32_e32 v194, 1.0, v194
	v_add_f32_e32 v195, 1.0, v195
	v_add_f32_e32 v196, 1.0, v196
	v_add_f32_e32 v197, 1.0, v197
	v_add_f32_e32 v198, 1.0, v198
	v_add_f32_e32 v199, 1.0, v199
	v_rcp_f32_e32 v192, v192
	v_rcp_f32_e32 v193, v193
	v_rcp_f32_e32 v194, v194
	v_rcp_f32_e32 v195, v195
	v_rcp_f32_e32 v196, v196
	v_rcp_f32_e32 v197, v197
	v_rcp_f32_e32 v198, v198
	v_rcp_f32_e32 v199, v199
	v_pk_mul_f32 v[92:93], v[92:93], v[192:193]
	v_pk_mul_f32 v[94:95], v[94:95], v[194:195]
	v_pk_mul_f32 v[88:89], v[88:89], v[196:197]
	v_pk_mul_f32 v[90:91], v[90:91], v[198:199]
	v_pk_mul_f32 v[92:93], v[84:85], v[92:93]
	v_pk_mul_f32 v[94:95], v[86:87], v[94:95]
	v_pk_mul_f32 v[88:89], v[80:81], v[88:89]
	v_pk_mul_f32 v[90:91], v[82:83], v[90:91]
	v_cvt_pk_bf16_f32 v208, v92, v93
	v_cvt_pk_bf16_f32 v209, v94, v95
	v_cvt_pk_bf16_f32 v210, v88, v89
	v_cvt_pk_bf16_f32 v211, v90, v91
	s_mov_b64 s[100:101], 0x2c000
	v_lshl_add_u64 v[216:217], v[232:233], 0, s[100:101]
	global_store_dwordx4 v[216:217], v[208:211], off
	s_waitcnt lgkmcnt(4)
	v_pk_mul_f32 v[76:77], v[76:77], v[178:179] op_sel_hi:[1,0]
	v_pk_mul_f32 v[78:79], v[78:79], v[178:179] op_sel_hi:[1,0]
	v_pk_mul_f32 v[72:73], v[72:73], v[178:179] op_sel_hi:[1,0]
	v_pk_mul_f32 v[74:75], v[74:75], v[178:179] op_sel_hi:[1,0]
	v_pk_mul_f32 v[68:69], v[68:69], v[178:179] op_sel_hi:[1,0]
	v_pk_mul_f32 v[70:71], v[70:71], v[178:179] op_sel_hi:[1,0]
	v_pk_mul_f32 v[64:65], v[64:65], v[178:179] op_sel_hi:[1,0]
	v_pk_mul_f32 v[66:67], v[66:67], v[178:179] op_sel_hi:[1,0]
	v_pk_mul_f32 v[200:201], v[76:77], v[188:189] op_sel_hi:[1,0]
	v_pk_mul_f32 v[202:203], v[78:79], v[188:189] op_sel_hi:[1,0]
	v_pk_mul_f32 v[204:205], v[72:73], v[188:189] op_sel_hi:[1,0]
	v_pk_mul_f32 v[206:207], v[74:75], v[188:189] op_sel_hi:[1,0]
	v_exp_f32_e32 v200, v200
	v_exp_f32_e32 v201, v201
	v_exp_f32_e32 v202, v202
	v_exp_f32_e32 v203, v203
	v_exp_f32_e32 v204, v204
	v_exp_f32_e32 v205, v205
	v_exp_f32_e32 v206, v206
	v_exp_f32_e32 v207, v207
	v_add_f32_e32 v200, 1.0, v200
	v_add_f32_e32 v201, 1.0, v201
	v_add_f32_e32 v202, 1.0, v202
	v_add_f32_e32 v203, 1.0, v203
	v_add_f32_e32 v204, 1.0, v204
	v_add_f32_e32 v205, 1.0, v205
	v_add_f32_e32 v206, 1.0, v206
	v_add_f32_e32 v207, 1.0, v207
	v_rcp_f32_e32 v200, v200
	v_rcp_f32_e32 v201, v201
	v_rcp_f32_e32 v202, v202
	v_rcp_f32_e32 v203, v203
	v_rcp_f32_e32 v204, v204
	v_rcp_f32_e32 v205, v205
	v_rcp_f32_e32 v206, v206
	v_rcp_f32_e32 v207, v207
	v_pk_mul_f32 v[76:77], v[76:77], v[200:201]
	v_pk_mul_f32 v[78:79], v[78:79], v[202:203]
	v_pk_mul_f32 v[72:73], v[72:73], v[204:205]
	v_pk_mul_f32 v[74:75], v[74:75], v[206:207]
	v_pk_mul_f32 v[76:77], v[68:69], v[76:77]
	v_pk_mul_f32 v[78:79], v[70:71], v[78:79]
	v_pk_mul_f32 v[72:73], v[64:65], v[72:73]
	v_pk_mul_f32 v[74:75], v[66:67], v[74:75]
	v_cvt_pk_bf16_f32 v212, v76, v77
	v_cvt_pk_bf16_f32 v213, v78, v79
	v_cvt_pk_bf16_f32 v214, v72, v73
	v_cvt_pk_bf16_f32 v215, v74, v75
	s_mov_b64 s[100:101], 0x42000
	v_lshl_add_u64 v[216:217], v[232:233], 0, s[100:101]
	global_store_dwordx4 v[216:217], v[212:215], off
	s_waitcnt lgkmcnt(3)
	v_pk_mul_f32 v[60:61], v[60:61], v[180:181] op_sel_hi:[1,0]
	v_pk_mul_f32 v[62:63], v[62:63], v[180:181] op_sel_hi:[1,0]
	v_pk_mul_f32 v[56:57], v[56:57], v[180:181] op_sel_hi:[1,0]
	v_pk_mul_f32 v[58:59], v[58:59], v[180:181] op_sel_hi:[1,0]
	v_pk_mul_f32 v[52:53], v[52:53], v[180:181] op_sel_hi:[1,0]
	v_pk_mul_f32 v[54:55], v[54:55], v[180:181] op_sel_hi:[1,0]
	v_pk_mul_f32 v[48:49], v[48:49], v[180:181] op_sel_hi:[1,0]
	v_pk_mul_f32 v[50:51], v[50:51], v[180:181] op_sel_hi:[1,0]
	v_pk_mul_f32 v[192:193], v[60:61], v[188:189] op_sel_hi:[1,0]
	v_pk_mul_f32 v[194:195], v[62:63], v[188:189] op_sel_hi:[1,0]
	v_pk_mul_f32 v[196:197], v[56:57], v[188:189] op_sel_hi:[1,0]
	v_pk_mul_f32 v[198:199], v[58:59], v[188:189] op_sel_hi:[1,0]
	v_exp_f32_e32 v192, v192
	v_exp_f32_e32 v193, v193
	v_exp_f32_e32 v194, v194
	v_exp_f32_e32 v195, v195
	v_exp_f32_e32 v196, v196
	v_exp_f32_e32 v197, v197
	v_exp_f32_e32 v198, v198
	v_exp_f32_e32 v199, v199
	v_add_f32_e32 v192, 1.0, v192
	v_add_f32_e32 v193, 1.0, v193
	v_add_f32_e32 v194, 1.0, v194
	v_add_f32_e32 v195, 1.0, v195
	v_add_f32_e32 v196, 1.0, v196
	v_add_f32_e32 v197, 1.0, v197
	v_add_f32_e32 v198, 1.0, v198
	v_add_f32_e32 v199, 1.0, v199
	v_rcp_f32_e32 v192, v192
	v_rcp_f32_e32 v193, v193
	v_rcp_f32_e32 v194, v194
	v_rcp_f32_e32 v195, v195
	v_rcp_f32_e32 v196, v196
	v_rcp_f32_e32 v197, v197
	v_rcp_f32_e32 v198, v198
	v_rcp_f32_e32 v199, v199
	v_pk_mul_f32 v[60:61], v[60:61], v[192:193]
	v_pk_mul_f32 v[62:63], v[62:63], v[194:195]
	v_pk_mul_f32 v[56:57], v[56:57], v[196:197]
	v_pk_mul_f32 v[58:59], v[58:59], v[198:199]
	v_pk_mul_f32 v[60:61], v[52:53], v[60:61]
	v_pk_mul_f32 v[62:63], v[54:55], v[62:63]
	v_pk_mul_f32 v[56:57], v[48:49], v[56:57]
	v_pk_mul_f32 v[58:59], v[50:51], v[58:59]
	v_cvt_pk_bf16_f32 v208, v60, v61
	v_cvt_pk_bf16_f32 v209, v62, v63
	v_cvt_pk_bf16_f32 v210, v56, v57
	v_cvt_pk_bf16_f32 v211, v58, v59
	s_mov_b64 s[100:101], 0xb0000
	v_lshl_add_u64 v[216:217], v[232:233], 0, s[100:101]
	global_store_dwordx4 v[216:217], v[208:211], off
	s_waitcnt lgkmcnt(2)
	v_pk_mul_f32 v[44:45], v[44:45], v[182:183] op_sel_hi:[1,0]
	v_pk_mul_f32 v[46:47], v[46:47], v[182:183] op_sel_hi:[1,0]
	v_pk_mul_f32 v[40:41], v[40:41], v[182:183] op_sel_hi:[1,0]
	v_pk_mul_f32 v[42:43], v[42:43], v[182:183] op_sel_hi:[1,0]
	v_pk_mul_f32 v[36:37], v[36:37], v[182:183] op_sel_hi:[1,0]
	v_pk_mul_f32 v[38:39], v[38:39], v[182:183] op_sel_hi:[1,0]
	v_pk_mul_f32 v[32:33], v[32:33], v[182:183] op_sel_hi:[1,0]
	v_pk_mul_f32 v[34:35], v[34:35], v[182:183] op_sel_hi:[1,0]
	v_pk_mul_f32 v[200:201], v[44:45], v[188:189] op_sel_hi:[1,0]
	v_pk_mul_f32 v[202:203], v[46:47], v[188:189] op_sel_hi:[1,0]
	v_pk_mul_f32 v[204:205], v[40:41], v[188:189] op_sel_hi:[1,0]
	v_pk_mul_f32 v[206:207], v[42:43], v[188:189] op_sel_hi:[1,0]
	v_exp_f32_e32 v200, v200
	v_exp_f32_e32 v201, v201
	v_exp_f32_e32 v202, v202
	v_exp_f32_e32 v203, v203
	v_exp_f32_e32 v204, v204
	v_exp_f32_e32 v205, v205
	v_exp_f32_e32 v206, v206
	v_exp_f32_e32 v207, v207
	v_add_f32_e32 v200, 1.0, v200
	v_add_f32_e32 v201, 1.0, v201
	v_add_f32_e32 v202, 1.0, v202
	v_add_f32_e32 v203, 1.0, v203
	v_add_f32_e32 v204, 1.0, v204
	v_add_f32_e32 v205, 1.0, v205
	v_add_f32_e32 v206, 1.0, v206
	v_add_f32_e32 v207, 1.0, v207
	v_rcp_f32_e32 v200, v200
	v_rcp_f32_e32 v201, v201
	v_rcp_f32_e32 v202, v202
	v_rcp_f32_e32 v203, v203
	v_rcp_f32_e32 v204, v204
	v_rcp_f32_e32 v205, v205
	v_rcp_f32_e32 v206, v206
	v_rcp_f32_e32 v207, v207
	v_pk_mul_f32 v[44:45], v[44:45], v[200:201]
	v_pk_mul_f32 v[46:47], v[46:47], v[202:203]
	v_pk_mul_f32 v[40:41], v[40:41], v[204:205]
	v_pk_mul_f32 v[42:43], v[42:43], v[206:207]
	v_pk_mul_f32 v[44:45], v[36:37], v[44:45]
	v_pk_mul_f32 v[46:47], v[38:39], v[46:47]
	v_pk_mul_f32 v[40:41], v[32:33], v[40:41]
	v_pk_mul_f32 v[42:43], v[34:35], v[42:43]
	v_cvt_pk_bf16_f32 v212, v44, v45
	v_cvt_pk_bf16_f32 v213, v46, v47
	v_cvt_pk_bf16_f32 v214, v40, v41
	v_cvt_pk_bf16_f32 v215, v42, v43
	s_mov_b64 s[100:101], 0xc6000
	v_lshl_add_u64 v[216:217], v[232:233], 0, s[100:101]
	global_store_dwordx4 v[216:217], v[212:215], off
	s_waitcnt lgkmcnt(1)
	v_pk_mul_f32 v[28:29], v[28:29], v[184:185] op_sel_hi:[1,0]
	v_pk_mul_f32 v[30:31], v[30:31], v[184:185] op_sel_hi:[1,0]
	v_pk_mul_f32 v[24:25], v[24:25], v[184:185] op_sel_hi:[1,0]
	v_pk_mul_f32 v[26:27], v[26:27], v[184:185] op_sel_hi:[1,0]
	v_pk_mul_f32 v[20:21], v[20:21], v[184:185] op_sel_hi:[1,0]
	v_pk_mul_f32 v[22:23], v[22:23], v[184:185] op_sel_hi:[1,0]
	v_pk_mul_f32 v[16:17], v[16:17], v[184:185] op_sel_hi:[1,0]
	v_pk_mul_f32 v[18:19], v[18:19], v[184:185] op_sel_hi:[1,0]
	v_pk_mul_f32 v[192:193], v[28:29], v[188:189] op_sel_hi:[1,0]
	v_pk_mul_f32 v[194:195], v[30:31], v[188:189] op_sel_hi:[1,0]
	v_pk_mul_f32 v[196:197], v[24:25], v[188:189] op_sel_hi:[1,0]
	v_pk_mul_f32 v[198:199], v[26:27], v[188:189] op_sel_hi:[1,0]
	v_exp_f32_e32 v192, v192
	v_exp_f32_e32 v193, v193
	v_exp_f32_e32 v194, v194
	v_exp_f32_e32 v195, v195
	v_exp_f32_e32 v196, v196
	v_exp_f32_e32 v197, v197
	v_exp_f32_e32 v198, v198
	v_exp_f32_e32 v199, v199
	v_add_f32_e32 v192, 1.0, v192
	v_add_f32_e32 v193, 1.0, v193
	v_add_f32_e32 v194, 1.0, v194
	v_add_f32_e32 v195, 1.0, v195
	v_add_f32_e32 v196, 1.0, v196
	v_add_f32_e32 v197, 1.0, v197
	v_add_f32_e32 v198, 1.0, v198
	v_add_f32_e32 v199, 1.0, v199
	v_rcp_f32_e32 v192, v192
	v_rcp_f32_e32 v193, v193
	v_rcp_f32_e32 v194, v194
	v_rcp_f32_e32 v195, v195
	v_rcp_f32_e32 v196, v196
	v_rcp_f32_e32 v197, v197
	v_rcp_f32_e32 v198, v198
	v_rcp_f32_e32 v199, v199
	v_pk_mul_f32 v[28:29], v[28:29], v[192:193]
	v_pk_mul_f32 v[30:31], v[30:31], v[194:195]
	v_pk_mul_f32 v[24:25], v[24:25], v[196:197]
	v_pk_mul_f32 v[26:27], v[26:27], v[198:199]
	v_pk_mul_f32 v[28:29], v[20:21], v[28:29]
	v_pk_mul_f32 v[30:31], v[22:23], v[30:31]
	v_pk_mul_f32 v[24:25], v[16:17], v[24:25]
	v_pk_mul_f32 v[26:27], v[18:19], v[26:27]
	v_cvt_pk_bf16_f32 v208, v28, v29
	v_cvt_pk_bf16_f32 v209, v30, v31
	v_cvt_pk_bf16_f32 v210, v24, v25
	v_cvt_pk_bf16_f32 v211, v26, v27
	s_mov_b64 s[100:101], 0xdc000
	v_lshl_add_u64 v[216:217], v[232:233], 0, s[100:101]
	global_store_dwordx4 v[216:217], v[208:211], off
	s_waitcnt lgkmcnt(0)
	v_pk_mul_f32 v[12:13], v[12:13], v[186:187] op_sel_hi:[1,0]
	v_pk_mul_f32 v[14:15], v[14:15], v[186:187] op_sel_hi:[1,0]
	v_pk_mul_f32 v[8:9], v[8:9], v[186:187] op_sel_hi:[1,0]
	v_pk_mul_f32 v[10:11], v[10:11], v[186:187] op_sel_hi:[1,0]
	v_pk_mul_f32 v[4:5], v[4:5], v[186:187] op_sel_hi:[1,0]
	v_pk_mul_f32 v[6:7], v[6:7], v[186:187] op_sel_hi:[1,0]
	v_pk_mul_f32 v[0:1], v[0:1], v[186:187] op_sel_hi:[1,0]
	v_pk_mul_f32 v[2:3], v[2:3], v[186:187] op_sel_hi:[1,0]
	v_pk_mul_f32 v[200:201], v[12:13], v[188:189] op_sel_hi:[1,0]
	v_pk_mul_f32 v[202:203], v[14:15], v[188:189] op_sel_hi:[1,0]
	v_pk_mul_f32 v[204:205], v[8:9], v[188:189] op_sel_hi:[1,0]
	v_pk_mul_f32 v[206:207], v[10:11], v[188:189] op_sel_hi:[1,0]
	v_exp_f32_e32 v200, v200
	v_exp_f32_e32 v201, v201
	v_exp_f32_e32 v202, v202
	v_exp_f32_e32 v203, v203
	v_exp_f32_e32 v204, v204
	v_exp_f32_e32 v205, v205
	v_exp_f32_e32 v206, v206
	v_exp_f32_e32 v207, v207
	v_add_f32_e32 v200, 1.0, v200
	v_add_f32_e32 v201, 1.0, v201
	v_add_f32_e32 v202, 1.0, v202
	v_add_f32_e32 v203, 1.0, v203
	v_add_f32_e32 v204, 1.0, v204
	v_add_f32_e32 v205, 1.0, v205
	v_add_f32_e32 v206, 1.0, v206
	v_add_f32_e32 v207, 1.0, v207
	v_rcp_f32_e32 v200, v200
	v_rcp_f32_e32 v201, v201
	v_rcp_f32_e32 v202, v202
	v_rcp_f32_e32 v203, v203
	v_rcp_f32_e32 v204, v204
	v_rcp_f32_e32 v205, v205
	v_rcp_f32_e32 v206, v206
	v_rcp_f32_e32 v207, v207
	v_pk_mul_f32 v[12:13], v[12:13], v[200:201]
	v_pk_mul_f32 v[14:15], v[14:15], v[202:203]
	v_pk_mul_f32 v[8:9], v[8:9], v[204:205]
	v_pk_mul_f32 v[10:11], v[10:11], v[206:207]
	v_pk_mul_f32 v[12:13], v[4:5], v[12:13]
	v_pk_mul_f32 v[14:15], v[6:7], v[14:15]
	v_pk_mul_f32 v[8:9], v[0:1], v[8:9]
	v_pk_mul_f32 v[10:11], v[2:3], v[10:11]
	v_cvt_pk_bf16_f32 v212, v12, v13
	v_cvt_pk_bf16_f32 v213, v14, v15
	v_cvt_pk_bf16_f32 v214, v8, v9
	v_cvt_pk_bf16_f32 v215, v10, v11
	s_mov_b64 s[100:101], 0xf2000
	v_lshl_add_u64 v[216:217], v[232:233], 0, s[100:101]
	global_store_dwordx4 v[216:217], v[212:215], off
	s_andn2_b64 vcc, exec, s[4:5]
	s_mov_b64 s[4:5], -1
	s_cbranch_vccnz .LBB0_2087
	s_andn2_b64 vcc, exec, s[0:1]
	s_cbranch_vccnz .LBB0_2086
	s_nop 0
	s_branch .LBB0_2086
